# hand-written ffnconv v3 (layer 0): earlier prefetch, 64-token context items, static first item
# speedup vs baseline: 1.0172x; 1.0172x over previous
.LBB0_1249:
.LBB0_1250:
	s_waitcnt vmcnt(0) lgkmcnt(0)
	s_load_dwordx4 s[0:3], s[92:93], 0xd8
	s_add_u32 s38, s90, 0x15918000
	s_addc_u32 s39, s91, 0
	s_add_u32 s40, s90, 0x21918000
	s_addc_u32 s41, s91, 0
	s_add_u32 s4, s90, 0x2c918080
	s_addc_u32 s5, s91, 0
	v_mov_b32_e32 v4, 0xbfb8aa3b
	v_mov_b32_e32 v5, 0xbfb8aa3b
	v_mov_b32_e32 v6, 1.0
	v_mov_b32_e32 v7, 1.0
	v_mov_b32_e32 v9, 0
	v_mov_b32_e32 v208, 1
	s_waitcnt lgkmcnt(0)
	v_readfirstlane_b32 s6, v154
	s_lshr_b32 s6, s6, 6
	s_lshl_b32 s6, s6, 8
	s_add_u32 s6, s6, s96
.Lffn_p9_item:
	s_cmp_ge_u32 s6, 4224
	s_cbranch_scc1 .Lffn_p9_done
	s_mov_b64 s[44:45], exec
	s_mov_b64 exec, 1
	global_atomic_add v8, v9, v208, s[4:5] sc0
	s_mov_b64 exec, s[44:45]
	s_cmp_ge_u32 s6, 1408
	s_cbranch_scc1 .Lffn_p9_ctx
	s_mul_i32 s33, s6, 47663
	s_lshr_b32 s33, s33, 21
	s_mul_i32 s34, s33, 44
	s_sub_u32 s43, s6, s34
	s_and_b32 s34, s33, 1
	s_bfe_u32 s35, s33, 0x20001
	s_lshr_b32 s36, s33, 3
	s_cmp_lg_u32 s35, 0
	s_cselect_b32 s28, -1, 0
	s_cmp_lg_u32 s35, 3
	s_cselect_b32 s29, -1, 0
	s_cmp_lg_u32 s34, 0
	s_cselect_b32 s30, -1, 0
	s_cselect_b32 s31, 0, -1
	s_lshl_b32 s36, s36, 10
	s_lshl_b32 s35, s35, 8
	s_lshl_b32 s34, s34, 5
	s_add_u32 s36, s36, s35
	s_add_u32 s36, s36, s34
	s_add_u32 s36, s36, 4096
	v_and_b32_e32 v1, 63, v154
	v_lshlrev_b32_e32 v1, 2, v1
	s_lshl_b32 s33, s43, 8
	v_add_u32_e32 v1, s33, v1
	v_add_u32_e32 v2, 0x2c00, v1
	v_lshlrev_b32_e32 v3, 1, v1
	s_add_i32 s33, s36, 0
	s_mul_i32 s33, s33, 0x2c00
	s_add_u32 s20, s40, s33
	s_addc_u32 s21, s41, 0
	s_add_i32 s33, s36, 64
	s_mul_i32 s33, s33, 0x2c00
	s_add_u32 s22, s40, s33
	s_addc_u32 s23, s41, 0
	s_add_i32 s33, s36, 128
	s_mul_i32 s33, s33, 0x2c00
	s_add_u32 s24, s40, s33
	s_addc_u32 s25, s41, 0
	s_add_i32 s33, s36, 192
	s_mul_i32 s33, s33, 0x2c00
	s_add_u32 s26, s40, s33
	s_addc_u32 s27, s41, 0
	s_add_i32 s33, s36, -65
	s_mul_i32 s33, s33, 0x5800
	s_ashr_i32 s34, s33, 31
	s_add_u32 s8, s38, s33
	s_addc_u32 s9, s39, s34
	s_add_i32 s33, s36, -1
	s_mul_i32 s33, s33, 0x5800
	s_ashr_i32 s34, s33, 31
	s_add_u32 s10, s38, s33
	s_addc_u32 s11, s39, s34
	s_add_i32 s33, s36, 63
	s_mul_i32 s33, s33, 0x5800
	s_ashr_i32 s34, s33, 31
	s_add_u32 s12, s38, s33
	s_addc_u32 s13, s39, s34
	s_add_i32 s33, s36, 127
	s_mul_i32 s33, s33, 0x5800
	s_ashr_i32 s34, s33, 31
	s_add_u32 s14, s38, s33
	s_addc_u32 s15, s39, s34
	s_add_i32 s33, s36, 191
	s_mul_i32 s33, s33, 0x5800
	s_ashr_i32 s34, s33, 31
	s_add_u32 s16, s38, s33
	s_addc_u32 s17, s39, s34
	s_add_i32 s33, s36, 255
	s_mul_i32 s33, s33, 0x5800
	s_ashr_i32 s34, s33, 31
	s_add_u32 s18, s38, s33
	s_addc_u32 s19, s39, s34
	s_add_u32 s33, s0, 0x0
	s_addc_u32 s34, s1, 0
	s_mov_b32 s36, s33
	s_mov_b32 s37, s34
	global_load_dwordx2 v[10:11], v3, s[36:37]
	s_add_u32 s36, s36, 0x5800
	s_addc_u32 s37, s37, 0
	global_load_dwordx2 v[28:29], v3, s[36:37]
	s_add_u32 s33, s0, 0xb000
	s_addc_u32 s34, s1, 0
	s_mov_b32 s36, s33
	s_mov_b32 s37, s34
	global_load_dwordx2 v[12:13], v3, s[36:37]
	s_add_u32 s36, s36, 0x5800
	s_addc_u32 s37, s37, 0
	global_load_dwordx2 v[30:31], v3, s[36:37]
	s_add_u32 s33, s0, 0x16000
	s_addc_u32 s34, s1, 0
	s_mov_b32 s36, s33
	s_mov_b32 s37, s34
	global_load_dwordx2 v[14:15], v3, s[36:37]
	s_add_u32 s36, s36, 0x5800
	s_addc_u32 s37, s37, 0
	global_load_dwordx2 v[32:33], v3, s[36:37]
	s_add_u32 s33, s0, 0x21000
	s_addc_u32 s34, s1, 0
	s_mov_b32 s36, s33
	s_mov_b32 s37, s34
	global_load_dwordx2 v[16:17], v3, s[36:37]
	s_add_u32 s36, s36, 0x5800
	s_addc_u32 s37, s37, 0
	global_load_dwordx2 v[34:35], v3, s[36:37]
	s_add_u32 s33, s0, 0x2c000
	s_addc_u32 s34, s1, 0
	s_mov_b32 s36, s33
	s_mov_b32 s37, s34
	global_load_dwordx2 v[18:19], v3, s[36:37]
	s_add_u32 s36, s36, 0x5800
	s_addc_u32 s37, s37, 0
	global_load_dwordx2 v[36:37], v3, s[36:37]
	s_add_u32 s33, s0, 0x37000
	s_addc_u32 s34, s1, 0
	s_mov_b32 s36, s33
	s_mov_b32 s37, s34
	global_load_dwordx2 v[20:21], v3, s[36:37]
	s_add_u32 s36, s36, 0x5800
	s_addc_u32 s37, s37, 0
	global_load_dwordx2 v[38:39], v3, s[36:37]
	s_add_u32 s33, s0, 0x42000
	s_addc_u32 s34, s1, 0
	s_mov_b32 s36, s33
	s_mov_b32 s37, s34
	global_load_dwordx2 v[22:23], v3, s[36:37]
	s_add_u32 s36, s36, 0x5800
	s_addc_u32 s37, s37, 0
	global_load_dwordx2 v[40:41], v3, s[36:37]
	s_add_u32 s33, s0, 0x4d000
	s_addc_u32 s34, s1, 0
	s_mov_b32 s36, s33
	s_mov_b32 s37, s34
	global_load_dwordx2 v[24:25], v3, s[36:37]
	s_add_u32 s36, s36, 0x5800
	s_addc_u32 s37, s37, 0
	global_load_dwordx2 v[42:43], v3, s[36:37]
	s_add_u32 s33, s0, 0x58000
	s_addc_u32 s34, s1, 0
	s_mov_b32 s36, s33
	s_mov_b32 s37, s34
	global_load_dwordx2 v[26:27], v3, s[36:37]
	s_add_u32 s36, s36, 0x5800
	s_addc_u32 s37, s37, 0
	global_load_dwordx2 v[44:45], v3, s[36:37]
	global_load_dwordx2 v[46:47], v3, s[2:3]
	s_add_u32 s36, s2, 0x5800
	s_addc_u32 s37, s3, 0
	global_load_dwordx2 v[48:49], v3, s[36:37]
	global_load_dword v180, v1, s[8:9]
	global_load_dword v181, v2, s[8:9]
	global_load_dword v182, v1, s[10:11]
	global_load_dword v183, v2, s[10:11]
	global_load_dword v184, v1, s[12:13]
	global_load_dword v185, v2, s[12:13]
	global_load_dword v186, v1, s[14:15]
	global_load_dword v187, v2, s[14:15]
	global_load_dword v188, v1, s[16:17]
	global_load_dword v189, v2, s[16:17]
	global_load_dword v190, v1, s[18:19]
	global_load_dword v191, v2, s[18:19]
	s_add_u32 s8, s8, 0x5800
	s_addc_u32 s9, s9, 0
	s_add_u32 s10, s10, 0x5800
	s_addc_u32 s11, s11, 0
	s_add_u32 s12, s12, 0x5800
	s_addc_u32 s13, s13, 0
	s_add_u32 s14, s14, 0x5800
	s_addc_u32 s15, s15, 0
	s_add_u32 s16, s16, 0x5800
	s_addc_u32 s17, s17, 0
	s_add_u32 s18, s18, 0x5800
	s_addc_u32 s19, s19, 0
	global_load_dword v192, v1, s[8:9]
	global_load_dword v193, v2, s[8:9]
	global_load_dword v194, v1, s[10:11]
	global_load_dword v195, v2, s[10:11]
	global_load_dword v196, v1, s[12:13]
	global_load_dword v197, v2, s[12:13]
	global_load_dword v198, v1, s[14:15]
	global_load_dword v199, v2, s[14:15]
	global_load_dword v200, v1, s[16:17]
	global_load_dword v201, v2, s[16:17]
	global_load_dword v202, v1, s[18:19]
	global_load_dword v203, v2, s[18:19]
	s_add_u32 s8, s8, 0x5800
	s_addc_u32 s9, s9, 0
	s_add_u32 s10, s10, 0x5800
	s_addc_u32 s11, s11, 0
	s_add_u32 s12, s12, 0x5800
	s_addc_u32 s13, s13, 0
	s_add_u32 s14, s14, 0x5800
	s_addc_u32 s15, s15, 0
	s_add_u32 s16, s16, 0x5800
	s_addc_u32 s17, s17, 0
	s_add_u32 s18, s18, 0x5800
	s_addc_u32 s19, s19, 0
	global_load_dword v156, v1, s[8:9]
	global_load_dword v157, v2, s[8:9]
	global_load_dword v158, v1, s[10:11]
	global_load_dword v159, v2, s[10:11]
	global_load_dword v160, v1, s[12:13]
	global_load_dword v161, v2, s[12:13]
	global_load_dword v162, v1, s[14:15]
	global_load_dword v163, v2, s[14:15]
	global_load_dword v164, v1, s[16:17]
	global_load_dword v165, v2, s[16:17]
	global_load_dword v166, v1, s[18:19]
	global_load_dword v167, v2, s[18:19]
	s_add_u32 s8, s8, 0x5800
	s_addc_u32 s9, s9, 0
	s_add_u32 s10, s10, 0x5800
	s_addc_u32 s11, s11, 0
	s_add_u32 s12, s12, 0x5800
	s_addc_u32 s13, s13, 0
	s_add_u32 s14, s14, 0x5800
	s_addc_u32 s15, s15, 0
	s_add_u32 s16, s16, 0x5800
	s_addc_u32 s17, s17, 0
	s_add_u32 s18, s18, 0x5800
	s_addc_u32 s19, s19, 0
	global_load_dword v168, v1, s[8:9]
	global_load_dword v169, v2, s[8:9]
	global_load_dword v170, v1, s[10:11]
	global_load_dword v171, v2, s[10:11]
	global_load_dword v172, v1, s[12:13]
	global_load_dword v173, v2, s[12:13]
	global_load_dword v174, v1, s[14:15]
	global_load_dword v175, v2, s[14:15]
	global_load_dword v176, v1, s[16:17]
	global_load_dword v177, v2, s[16:17]
	global_load_dword v178, v1, s[18:19]
	global_load_dword v179, v2, s[18:19]
	s_add_u32 s8, s8, 0x5800
	s_addc_u32 s9, s9, 0
	s_add_u32 s10, s10, 0x5800
	s_addc_u32 s11, s11, 0
	s_add_u32 s12, s12, 0x5800
	s_addc_u32 s13, s13, 0
	s_add_u32 s14, s14, 0x5800
	s_addc_u32 s15, s15, 0
	s_add_u32 s16, s16, 0x5800
	s_addc_u32 s17, s17, 0
	s_add_u32 s18, s18, 0x5800
	s_addc_u32 s19, s19, 0
	s_waitcnt vmcnt(24)
	v_and_b32_e32 v180, s30, v180
	v_and_b32_e32 v181, s30, v181
	v_and_b32_e32 v180, s28, v180
	v_and_b32_e32 v181, s28, v181
	v_lshlrev_b32_e32 v50, 16, v180
	v_and_b32_e32 v51, 0xffff0000, v180
	v_lshlrev_b32_e32 v52, 16, v181
	v_and_b32_e32 v53, 0xffff0000, v181
	v_and_b32_e32 v182, s30, v182
	v_and_b32_e32 v183, s30, v183
	v_lshlrev_b32_e32 v54, 16, v182
	v_and_b32_e32 v55, 0xffff0000, v182
	v_lshlrev_b32_e32 v56, 16, v183
	v_and_b32_e32 v57, 0xffff0000, v183
	v_and_b32_e32 v184, s30, v184
	v_and_b32_e32 v185, s30, v185
	v_lshlrev_b32_e32 v58, 16, v184
	v_and_b32_e32 v59, 0xffff0000, v184
	v_lshlrev_b32_e32 v60, 16, v185
	v_and_b32_e32 v61, 0xffff0000, v185
	v_and_b32_e32 v186, s30, v186
	v_and_b32_e32 v187, s30, v187
	v_lshlrev_b32_e32 v62, 16, v186
	v_and_b32_e32 v63, 0xffff0000, v186
	v_lshlrev_b32_e32 v64, 16, v187
	v_and_b32_e32 v65, 0xffff0000, v187
	v_and_b32_e32 v188, s30, v188
	v_and_b32_e32 v189, s30, v189
	v_lshlrev_b32_e32 v66, 16, v188
	v_and_b32_e32 v67, 0xffff0000, v188
	v_lshlrev_b32_e32 v68, 16, v189
	v_and_b32_e32 v69, 0xffff0000, v189
	v_and_b32_e32 v190, s30, v190
	v_and_b32_e32 v191, s30, v191
	v_and_b32_e32 v190, s29, v190
	v_and_b32_e32 v191, s29, v191
	v_lshlrev_b32_e32 v70, 16, v190
	v_and_b32_e32 v71, 0xffff0000, v190
	v_lshlrev_b32_e32 v72, 16, v191
	v_and_b32_e32 v73, 0xffff0000, v191
	v_and_b32_e32 v192, s28, v192
	v_and_b32_e32 v193, s28, v193
	v_lshlrev_b32_e32 v74, 16, v192
	v_and_b32_e32 v75, 0xffff0000, v192
	v_lshlrev_b32_e32 v76, 16, v193
	v_and_b32_e32 v77, 0xffff0000, v193
	v_lshlrev_b32_e32 v78, 16, v194
	v_and_b32_e32 v79, 0xffff0000, v194
	v_lshlrev_b32_e32 v80, 16, v195
	v_and_b32_e32 v81, 0xffff0000, v195
	v_lshlrev_b32_e32 v82, 16, v196
	v_and_b32_e32 v83, 0xffff0000, v196
	v_lshlrev_b32_e32 v84, 16, v197
	v_and_b32_e32 v85, 0xffff0000, v197
	v_lshlrev_b32_e32 v86, 16, v198
	v_and_b32_e32 v87, 0xffff0000, v198
	v_lshlrev_b32_e32 v88, 16, v199
	v_and_b32_e32 v89, 0xffff0000, v199
	v_lshlrev_b32_e32 v90, 16, v200
	v_and_b32_e32 v91, 0xffff0000, v200
	v_lshlrev_b32_e32 v92, 16, v201
	v_and_b32_e32 v93, 0xffff0000, v201
	v_and_b32_e32 v202, s29, v202
	v_and_b32_e32 v203, s29, v203
	v_lshlrev_b32_e32 v94, 16, v202
	v_and_b32_e32 v95, 0xffff0000, v202
	v_lshlrev_b32_e32 v96, 16, v203
	v_and_b32_e32 v97, 0xffff0000, v203
	global_load_dword v180, v1, s[8:9]
	global_load_dword v181, v2, s[8:9]
	global_load_dword v182, v1, s[10:11]
	global_load_dword v183, v2, s[10:11]
	global_load_dword v184, v1, s[12:13]
	global_load_dword v185, v2, s[12:13]
	global_load_dword v186, v1, s[14:15]
	global_load_dword v187, v2, s[14:15]
	global_load_dword v188, v1, s[16:17]
	global_load_dword v189, v2, s[16:17]
	global_load_dword v190, v1, s[18:19]
	global_load_dword v191, v2, s[18:19]
	s_add_u32 s8, s8, 0x5800
	s_addc_u32 s9, s9, 0
	s_add_u32 s10, s10, 0x5800
	s_addc_u32 s11, s11, 0
	s_add_u32 s12, s12, 0x5800
	s_addc_u32 s13, s13, 0
	s_add_u32 s14, s14, 0x5800
	s_addc_u32 s15, s15, 0
	s_add_u32 s16, s16, 0x5800
	s_addc_u32 s17, s17, 0
	s_add_u32 s18, s18, 0x5800
	s_addc_u32 s19, s19, 0
	global_load_dword v192, v1, s[8:9]
	global_load_dword v193, v2, s[8:9]
	global_load_dword v194, v1, s[10:11]
	global_load_dword v195, v2, s[10:11]
	global_load_dword v196, v1, s[12:13]
	global_load_dword v197, v2, s[12:13]
	global_load_dword v198, v1, s[14:15]
	global_load_dword v199, v2, s[14:15]
	global_load_dword v200, v1, s[16:17]
	global_load_dword v201, v2, s[16:17]
	global_load_dword v202, v1, s[18:19]
	global_load_dword v203, v2, s[18:19]
	s_add_u32 s8, s8, 0x5800
	s_addc_u32 s9, s9, 0
	s_add_u32 s10, s10, 0x5800
	s_addc_u32 s11, s11, 0
	s_add_u32 s12, s12, 0x5800
	s_addc_u32 s13, s13, 0
	s_add_u32 s14, s14, 0x5800
	s_addc_u32 s15, s15, 0
	s_add_u32 s16, s16, 0x5800
	s_addc_u32 s17, s17, 0
	s_add_u32 s18, s18, 0x5800
	s_addc_u32 s19, s19, 0
	s_mov_b32 s32, 0

.Lffn_p9_wn3:
	s_waitcnt vmcnt(40)
.Lffn_p9_we2:
	v_and_b32_e32 v156, s28, v156
	v_and_b32_e32 v157, s28, v157
	v_lshlrev_b32_e32 v98, 16, v156
	v_and_b32_e32 v99, 0xffff0000, v156
	v_lshlrev_b32_e32 v100, 16, v157
	v_and_b32_e32 v101, 0xffff0000, v157
	v_lshlrev_b32_e32 v102, 16, v158
	v_and_b32_e32 v103, 0xffff0000, v158
	v_lshlrev_b32_e32 v104, 16, v159
	v_and_b32_e32 v105, 0xffff0000, v159
	v_lshlrev_b32_e32 v106, 16, v160
	v_and_b32_e32 v107, 0xffff0000, v160
	v_lshlrev_b32_e32 v108, 16, v161
	v_and_b32_e32 v109, 0xffff0000, v161
	v_lshlrev_b32_e32 v110, 16, v162
	v_and_b32_e32 v111, 0xffff0000, v162
	v_lshlrev_b32_e32 v112, 16, v163
	v_and_b32_e32 v113, 0xffff0000, v163
	v_lshlrev_b32_e32 v114, 16, v164
	v_and_b32_e32 v115, 0xffff0000, v164
	v_lshlrev_b32_e32 v116, 16, v165
	v_and_b32_e32 v117, 0xffff0000, v165
	v_and_b32_e32 v166, s29, v166
	v_and_b32_e32 v167, s29, v167
	v_lshlrev_b32_e32 v118, 16, v166
	v_and_b32_e32 v119, 0xffff0000, v166
	v_lshlrev_b32_e32 v120, 16, v167
	v_and_b32_e32 v121, 0xffff0000, v167
	v_and_b32_e32 v168, s28, v168
	v_and_b32_e32 v169, s28, v169
	v_lshlrev_b32_e32 v122, 16, v168
	v_and_b32_e32 v123, 0xffff0000, v168
	v_lshlrev_b32_e32 v124, 16, v169
	v_and_b32_e32 v125, 0xffff0000, v169
	v_lshlrev_b32_e32 v126, 16, v170
	v_and_b32_e32 v127, 0xffff0000, v170
	v_lshlrev_b32_e32 v128, 16, v171
	v_and_b32_e32 v129, 0xffff0000, v171
	v_lshlrev_b32_e32 v130, 16, v172
	v_and_b32_e32 v131, 0xffff0000, v172
	v_lshlrev_b32_e32 v132, 16, v173
	v_and_b32_e32 v133, 0xffff0000, v173
	v_lshlrev_b32_e32 v134, 16, v174
	v_and_b32_e32 v135, 0xffff0000, v174
	v_lshlrev_b32_e32 v136, 16, v175
	v_and_b32_e32 v137, 0xffff0000, v175
	v_lshlrev_b32_e32 v138, 16, v176
	v_and_b32_e32 v139, 0xffff0000, v176
	v_lshlrev_b32_e32 v140, 16, v177
	v_and_b32_e32 v141, 0xffff0000, v177
	v_and_b32_e32 v178, s29, v178
	v_and_b32_e32 v179, s29, v179
	v_lshlrev_b32_e32 v142, 16, v178
	v_and_b32_e32 v143, 0xffff0000, v178
	v_lshlrev_b32_e32 v144, 16, v179
	v_and_b32_e32 v145, 0xffff0000, v179
	s_cmp_eq_u32 s32, 7
	s_cbranch_scc1 .Lffn_p9_skipld4
	global_load_dword v156, v1, s[8:9]
	global_load_dword v157, v2, s[8:9]
	global_load_dword v158, v1, s[10:11]
	global_load_dword v159, v2, s[10:11]
	global_load_dword v160, v1, s[12:13]
	global_load_dword v161, v2, s[12:13]
	global_load_dword v162, v1, s[14:15]
	global_load_dword v163, v2, s[14:15]
	global_load_dword v164, v1, s[16:17]
	global_load_dword v165, v2, s[16:17]
	global_load_dword v166, v1, s[18:19]
	global_load_dword v167, v2, s[18:19]
	s_add_u32 s8, s8, 0x5800
	s_addc_u32 s9, s9, 0
	s_add_u32 s10, s10, 0x5800
	s_addc_u32 s11, s11, 0
	s_add_u32 s12, s12, 0x5800
	s_addc_u32 s13, s13, 0
	s_add_u32 s14, s14, 0x5800
	s_addc_u32 s15, s15, 0
	s_add_u32 s16, s16, 0x5800
	s_addc_u32 s17, s17, 0
	s_add_u32 s18, s18, 0x5800
	s_addc_u32 s19, s19, 0
	global_load_dword v168, v1, s[8:9]
	global_load_dword v169, v2, s[8:9]
	global_load_dword v170, v1, s[10:11]
	global_load_dword v171, v2, s[10:11]
	global_load_dword v172, v1, s[12:13]
	global_load_dword v173, v2, s[12:13]
	global_load_dword v174, v1, s[14:15]
	global_load_dword v175, v2, s[14:15]
	global_load_dword v176, v1, s[16:17]
	global_load_dword v177, v2, s[16:17]
	global_load_dword v178, v1, s[18:19]
	global_load_dword v179, v2, s[18:19]
	s_add_u32 s8, s8, 0x5800
	s_addc_u32 s9, s9, 0
	s_add_u32 s10, s10, 0x5800
	s_addc_u32 s11, s11, 0
	s_add_u32 s12, s12, 0x5800
	s_addc_u32 s13, s13, 0
	s_add_u32 s14, s14, 0x5800
	s_addc_u32 s15, s15, 0
	s_add_u32 s16, s16, 0x5800
	s_addc_u32 s17, s17, 0
	s_add_u32 s18, s18, 0x5800
	s_addc_u32 s19, s19, 0
.Lffn_p9_skipld4:
	v_pk_fma_f32 v[146:147], v[10:11], v[50:51], v[46:47]
	v_pk_fma_f32 v[148:149], v[28:29], v[52:53], v[48:49]
	v_pk_fma_f32 v[146:147], v[12:13], v[74:75], v[146:147]
	v_pk_fma_f32 v[148:149], v[30:31], v[76:77], v[148:149]
	v_pk_fma_f32 v[146:147], v[14:15], v[98:99], v[146:147]
	v_pk_fma_f32 v[148:149], v[32:33], v[100:101], v[148:149]
	v_pk_fma_f32 v[146:147], v[16:17], v[54:55], v[146:147]
	v_pk_fma_f32 v[148:149], v[34:35], v[56:57], v[148:149]
	v_pk_fma_f32 v[146:147], v[18:19], v[78:79], v[146:147]
	v_pk_fma_f32 v[148:149], v[36:37], v[80:81], v[148:149]
	v_pk_fma_f32 v[146:147], v[20:21], v[102:103], v[146:147]
	v_pk_fma_f32 v[148:149], v[38:39], v[104:105], v[148:149]
	v_pk_fma_f32 v[146:147], v[22:23], v[58:59], v[146:147]
	v_pk_fma_f32 v[148:149], v[40:41], v[60:61], v[148:149]
	v_pk_fma_f32 v[146:147], v[24:25], v[82:83], v[146:147]
	v_pk_fma_f32 v[148:149], v[42:43], v[84:85], v[148:149]
	v_pk_fma_f32 v[146:147], v[26:27], v[106:107], v[146:147]
	v_pk_fma_f32 v[148:149], v[44:45], v[108:109], v[148:149]
	v_pk_mul_f32 v[150:151], v[146:147], v[4:5]
	v_exp_f32_e32 v150, v150
	v_exp_f32_e32 v151, v151
	s_nop 0
	v_pk_add_f32 v[150:151], v[150:151], v[6:7]
	v_rcp_f32_e32 v150, v150
	v_rcp_f32_e32 v151, v151
	s_nop 0
	v_pk_mul_f32 v[150:151], v[150:151], v[146:147]
	v_pk_mul_f32 v[150:151], v[150:151], v[148:149]
	v_cvt_pk_bf16_f32 v204, v150, v151
	global_store_dword v1, v204, s[20:21]
	v_pk_fma_f32 v[146:147], v[10:11], v[54:55], v[46:47]
	v_pk_fma_f32 v[148:149], v[28:29], v[56:57], v[48:49]
	v_pk_fma_f32 v[146:147], v[12:13], v[78:79], v[146:147]
	v_pk_fma_f32 v[148:149], v[30:31], v[80:81], v[148:149]
	v_pk_fma_f32 v[146:147], v[14:15], v[102:103], v[146:147]
	v_pk_fma_f32 v[148:149], v[32:33], v[104:105], v[148:149]
	v_pk_fma_f32 v[146:147], v[16:17], v[58:59], v[146:147]
	v_pk_fma_f32 v[148:149], v[34:35], v[60:61], v[148:149]
	v_pk_fma_f32 v[146:147], v[18:19], v[82:83], v[146:147]
	v_pk_fma_f32 v[148:149], v[36:37], v[84:85], v[148:149]
	v_pk_fma_f32 v[146:147], v[20:21], v[106:107], v[146:147]
	v_pk_fma_f32 v[148:149], v[38:39], v[108:109], v[148:149]
	v_pk_fma_f32 v[146:147], v[22:23], v[62:63], v[146:147]
	v_pk_fma_f32 v[148:149], v[40:41], v[64:65], v[148:149]
	v_pk_fma_f32 v[146:147], v[24:25], v[86:87], v[146:147]
	v_pk_fma_f32 v[148:149], v[42:43], v[88:89], v[148:149]
	v_pk_fma_f32 v[146:147], v[26:27], v[110:111], v[146:147]
	v_pk_fma_f32 v[148:149], v[44:45], v[112:113], v[148:149]
	v_pk_mul_f32 v[150:151], v[146:147], v[4:5]
	v_exp_f32_e32 v150, v150
	v_exp_f32_e32 v151, v151
	s_nop 0
	v_pk_add_f32 v[150:151], v[150:151], v[6:7]
	v_rcp_f32_e32 v150, v150
	v_rcp_f32_e32 v151, v151
	s_nop 0
	v_pk_mul_f32 v[150:151], v[150:151], v[146:147]
	v_pk_mul_f32 v[150:151], v[150:151], v[148:149]
	v_cvt_pk_bf16_f32 v205, v150, v151
	global_store_dword v1, v205, s[22:23]
	v_pk_fma_f32 v[146:147], v[10:11], v[58:59], v[46:47]
	v_pk_fma_f32 v[148:149], v[28:29], v[60:61], v[48:49]
	v_pk_fma_f32 v[146:147], v[12:13], v[82:83], v[146:147]
	v_pk_fma_f32 v[148:149], v[30:31], v[84:85], v[148:149]
	v_pk_fma_f32 v[146:147], v[14:15], v[106:107], v[146:147]
	v_pk_fma_f32 v[148:149], v[32:33], v[108:109], v[148:149]
	v_pk_fma_f32 v[146:147], v[16:17], v[62:63], v[146:147]
	v_pk_fma_f32 v[148:149], v[34:35], v[64:65], v[148:149]
	v_pk_fma_f32 v[146:147], v[18:19], v[86:87], v[146:147]
	v_pk_fma_f32 v[148:149], v[36:37], v[88:89], v[148:149]
	v_pk_fma_f32 v[146:147], v[20:21], v[110:111], v[146:147]
	v_pk_fma_f32 v[148:149], v[38:39], v[112:113], v[148:149]
	v_pk_fma_f32 v[146:147], v[22:23], v[66:67], v[146:147]
	v_pk_fma_f32 v[148:149], v[40:41], v[68:69], v[148:149]
	v_pk_fma_f32 v[146:147], v[24:25], v[90:91], v[146:147]
	v_pk_fma_f32 v[148:149], v[42:43], v[92:93], v[148:149]
	v_pk_fma_f32 v[146:147], v[26:27], v[114:115], v[146:147]
	v_pk_fma_f32 v[148:149], v[44:45], v[116:117], v[148:149]
	v_pk_mul_f32 v[150:151], v[146:147], v[4:5]
	v_exp_f32_e32 v150, v150
	v_exp_f32_e32 v151, v151
	s_nop 0
	v_pk_add_f32 v[150:151], v[150:151], v[6:7]
	v_rcp_f32_e32 v150, v150
	v_rcp_f32_e32 v151, v151
	s_nop 0
	v_pk_mul_f32 v[150:151], v[150:151], v[146:147]
	v_pk_mul_f32 v[150:151], v[150:151], v[148:149]
	v_cvt_pk_bf16_f32 v206, v150, v151
	global_store_dword v1, v206, s[24:25]
	v_pk_fma_f32 v[146:147], v[10:11], v[62:63], v[46:47]
	v_pk_fma_f32 v[148:149], v[28:29], v[64:65], v[48:49]
	v_pk_fma_f32 v[146:147], v[12:13], v[86:87], v[146:147]
	v_pk_fma_f32 v[148:149], v[30:31], v[88:89], v[148:149]
	v_pk_fma_f32 v[146:147], v[14:15], v[110:111], v[146:147]
	v_pk_fma_f32 v[148:149], v[32:33], v[112:113], v[148:149]
	v_pk_fma_f32 v[146:147], v[16:17], v[66:67], v[146:147]
	v_pk_fma_f32 v[148:149], v[34:35], v[68:69], v[148:149]
	v_pk_fma_f32 v[146:147], v[18:19], v[90:91], v[146:147]
	v_pk_fma_f32 v[148:149], v[36:37], v[92:93], v[148:149]
	v_pk_fma_f32 v[146:147], v[20:21], v[114:115], v[146:147]
	v_pk_fma_f32 v[148:149], v[38:39], v[116:117], v[148:149]
	v_pk_fma_f32 v[146:147], v[22:23], v[70:71], v[146:147]
	v_pk_fma_f32 v[148:149], v[40:41], v[72:73], v[148:149]
	v_pk_fma_f32 v[146:147], v[24:25], v[94:95], v[146:147]
	v_pk_fma_f32 v[148:149], v[42:43], v[96:97], v[148:149]
	v_pk_fma_f32 v[146:147], v[26:27], v[118:119], v[146:147]
	v_pk_fma_f32 v[148:149], v[44:45], v[120:121], v[148:149]
	v_pk_mul_f32 v[150:151], v[146:147], v[4:5]
	v_exp_f32_e32 v150, v150
	v_exp_f32_e32 v151, v151
	s_nop 0
	v_pk_add_f32 v[150:151], v[150:151], v[6:7]
	v_rcp_f32_e32 v150, v150
	v_rcp_f32_e32 v151, v151
	s_nop 0
	v_pk_mul_f32 v[150:151], v[150:151], v[146:147]
	v_pk_mul_f32 v[150:151], v[150:151], v[148:149]
	v_cvt_pk_bf16_f32 v207, v150, v151
	global_store_dword v1, v207, s[26:27]
	s_add_u32 s20, s20, 0x2c00
	s_addc_u32 s21, s21, 0
	s_add_u32 s22, s22, 0x2c00
	s_addc_u32 s23, s23, 0
	s_add_u32 s24, s24, 0x2c00
	s_addc_u32 s25, s25, 0
	s_add_u32 s26, s26, 0x2c00
	s_addc_u32 s27, s27, 0
	v_pk_fma_f32 v[146:147], v[10:11], v[74:75], v[46:47]
	v_pk_fma_f32 v[148:149], v[28:29], v[76:77], v[48:49]
	v_pk_fma_f32 v[146:147], v[12:13], v[98:99], v[146:147]
	v_pk_fma_f32 v[148:149], v[30:31], v[100:101], v[148:149]
	v_pk_fma_f32 v[146:147], v[14:15], v[122:123], v[146:147]
	v_pk_fma_f32 v[148:149], v[32:33], v[124:125], v[148:149]
	v_pk_fma_f32 v[146:147], v[16:17], v[78:79], v[146:147]
	v_pk_fma_f32 v[148:149], v[34:35], v[80:81], v[148:149]
	v_pk_fma_f32 v[146:147], v[18:19], v[102:103], v[146:147]
	v_pk_fma_f32 v[148:149], v[36:37], v[104:105], v[148:149]
	v_pk_fma_f32 v[146:147], v[20:21], v[126:127], v[146:147]
	v_pk_fma_f32 v[148:149], v[38:39], v[128:129], v[148:149]
	v_pk_fma_f32 v[146:147], v[22:23], v[82:83], v[146:147]
	v_pk_fma_f32 v[148:149], v[40:41], v[84:85], v[148:149]
	v_pk_fma_f32 v[146:147], v[24:25], v[106:107], v[146:147]
	v_pk_fma_f32 v[148:149], v[42:43], v[108:109], v[148:149]
	v_pk_fma_f32 v[146:147], v[26:27], v[130:131], v[146:147]
	v_pk_fma_f32 v[148:149], v[44:45], v[132:133], v[148:149]
	v_pk_mul_f32 v[150:151], v[146:147], v[4:5]
	v_exp_f32_e32 v150, v150
	v_exp_f32_e32 v151, v151
	s_nop 0
	v_pk_add_f32 v[150:151], v[150:151], v[6:7]
	v_rcp_f32_e32 v150, v150
	v_rcp_f32_e32 v151, v151
	s_nop 0
	v_pk_mul_f32 v[150:151], v[150:151], v[146:147]
	v_pk_mul_f32 v[150:151], v[150:151], v[148:149]
	v_cvt_pk_bf16_f32 v204, v150, v151
	global_store_dword v1, v204, s[20:21]
	v_pk_fma_f32 v[146:147], v[10:11], v[78:79], v[46:47]
	v_pk_fma_f32 v[148:149], v[28:29], v[80:81], v[48:49]
	v_pk_fma_f32 v[146:147], v[12:13], v[102:103], v[146:147]
	v_pk_fma_f32 v[148:149], v[30:31], v[104:105], v[148:149]
	v_pk_fma_f32 v[146:147], v[14:15], v[126:127], v[146:147]
	v_pk_fma_f32 v[148:149], v[32:33], v[128:129], v[148:149]
	v_pk_fma_f32 v[146:147], v[16:17], v[82:83], v[146:147]
	v_pk_fma_f32 v[148:149], v[34:35], v[84:85], v[148:149]
	v_pk_fma_f32 v[146:147], v[18:19], v[106:107], v[146:147]
	v_pk_fma_f32 v[148:149], v[36:37], v[108:109], v[148:149]
	v_pk_fma_f32 v[146:147], v[20:21], v[130:131], v[146:147]
	v_pk_fma_f32 v[148:149], v[38:39], v[132:133], v[148:149]
	v_pk_fma_f32 v[146:147], v[22:23], v[86:87], v[146:147]
	v_pk_fma_f32 v[148:149], v[40:41], v[88:89], v[148:149]
	v_pk_fma_f32 v[146:147], v[24:25], v[110:111], v[146:147]
	v_pk_fma_f32 v[148:149], v[42:43], v[112:113], v[148:149]
	v_pk_fma_f32 v[146:147], v[26:27], v[134:135], v[146:147]
	v_pk_fma_f32 v[148:149], v[44:45], v[136:137], v[148:149]
	v_pk_mul_f32 v[150:151], v[146:147], v[4:5]
	v_exp_f32_e32 v150, v150
	v_exp_f32_e32 v151, v151
	s_nop 0
	v_pk_add_f32 v[150:151], v[150:151], v[6:7]
	v_rcp_f32_e32 v150, v150
	v_rcp_f32_e32 v151, v151
	s_nop 0
	v_pk_mul_f32 v[150:151], v[150:151], v[146:147]
	v_pk_mul_f32 v[150:151], v[150:151], v[148:149]
	v_cvt_pk_bf16_f32 v205, v150, v151
	global_store_dword v1, v205, s[22:23]
	v_pk_fma_f32 v[146:147], v[10:11], v[82:83], v[46:47]
	v_pk_fma_f32 v[148:149], v[28:29], v[84:85], v[48:49]
	v_pk_fma_f32 v[146:147], v[12:13], v[106:107], v[146:147]
	v_pk_fma_f32 v[148:149], v[30:31], v[108:109], v[148:149]
	v_pk_fma_f32 v[146:147], v[14:15], v[130:131], v[146:147]
	v_pk_fma_f32 v[148:149], v[32:33], v[132:133], v[148:149]
	v_pk_fma_f32 v[146:147], v[16:17], v[86:87], v[146:147]
	v_pk_fma_f32 v[148:149], v[34:35], v[88:89], v[148:149]
	v_pk_fma_f32 v[146:147], v[18:19], v[110:111], v[146:147]
	v_pk_fma_f32 v[148:149], v[36:37], v[112:113], v[148:149]
	v_pk_fma_f32 v[146:147], v[20:21], v[134:135], v[146:147]
	v_pk_fma_f32 v[148:149], v[38:39], v[136:137], v[148:149]
	v_pk_fma_f32 v[146:147], v[22:23], v[90:91], v[146:147]
	v_pk_fma_f32 v[148:149], v[40:41], v[92:93], v[148:149]
	v_pk_fma_f32 v[146:147], v[24:25], v[114:115], v[146:147]
	v_pk_fma_f32 v[148:149], v[42:43], v[116:117], v[148:149]
	v_pk_fma_f32 v[146:147], v[26:27], v[138:139], v[146:147]
	v_pk_fma_f32 v[148:149], v[44:45], v[140:141], v[148:149]
	v_pk_mul_f32 v[150:151], v[146:147], v[4:5]
	v_exp_f32_e32 v150, v150
	v_exp_f32_e32 v151, v151
	s_nop 0
	v_pk_add_f32 v[150:151], v[150:151], v[6:7]
	v_rcp_f32_e32 v150, v150
	v_rcp_f32_e32 v151, v151
	s_nop 0
	v_pk_mul_f32 v[150:151], v[150:151], v[146:147]
	v_pk_mul_f32 v[150:151], v[150:151], v[148:149]
	v_cvt_pk_bf16_f32 v206, v150, v151
	global_store_dword v1, v206, s[24:25]
	v_pk_fma_f32 v[146:147], v[10:11], v[86:87], v[46:47]
	v_pk_fma_f32 v[148:149], v[28:29], v[88:89], v[48:49]
	v_pk_fma_f32 v[146:147], v[12:13], v[110:111], v[146:147]
	v_pk_fma_f32 v[148:149], v[30:31], v[112:113], v[148:149]
	v_pk_fma_f32 v[146:147], v[14:15], v[134:135], v[146:147]
	v_pk_fma_f32 v[148:149], v[32:33], v[136:137], v[148:149]
	v_pk_fma_f32 v[146:147], v[16:17], v[90:91], v[146:147]
	v_pk_fma_f32 v[148:149], v[34:35], v[92:93], v[148:149]
	v_pk_fma_f32 v[146:147], v[18:19], v[114:115], v[146:147]
	v_pk_fma_f32 v[148:149], v[36:37], v[116:117], v[148:149]
	v_pk_fma_f32 v[146:147], v[20:21], v[138:139], v[146:147]
	v_pk_fma_f32 v[148:149], v[38:39], v[140:141], v[148:149]
	v_pk_fma_f32 v[146:147], v[22:23], v[94:95], v[146:147]
	v_pk_fma_f32 v[148:149], v[40:41], v[96:97], v[148:149]
	v_pk_fma_f32 v[146:147], v[24:25], v[118:119], v[146:147]
	v_pk_fma_f32 v[148:149], v[42:43], v[120:121], v[148:149]
	v_pk_fma_f32 v[146:147], v[26:27], v[142:143], v[146:147]
	v_pk_fma_f32 v[148:149], v[44:45], v[144:145], v[148:149]
	v_pk_mul_f32 v[150:151], v[146:147], v[4:5]
	v_exp_f32_e32 v150, v150
	v_exp_f32_e32 v151, v151
	s_nop 0
	v_pk_add_f32 v[150:151], v[150:151], v[6:7]
	v_rcp_f32_e32 v150, v150
	v_rcp_f32_e32 v151, v151
	s_nop 0
	v_pk_mul_f32 v[150:151], v[150:151], v[146:147]
	v_pk_mul_f32 v[150:151], v[150:151], v[148:149]
	v_cvt_pk_bf16_f32 v207, v150, v151
	global_store_dword v1, v207, s[26:27]
	s_add_u32 s20, s20, 0x2c00
	s_addc_u32 s21, s21, 0
	s_add_u32 s22, s22, 0x2c00
	s_addc_u32 s23, s23, 0
	s_add_u32 s24, s24, 0x2c00
	s_addc_u32 s25, s25, 0
	s_add_u32 s26, s26, 0x2c00
	s_addc_u32 s27, s27, 0
	s_cmp_lg_u32 s32, 0
	s_cbranch_scc1 .Lffn_p9_wn6
	s_waitcnt vmcnt(32)
	s_branch .Lffn_p9_we5
.Lffn_p9_wn6:
	s_cmp_lg_u32 s32, 7
	s_cbranch_scc1 .Lffn_p9_wn7
	s_waitcnt vmcnt(16)
	s_branch .Lffn_p9_we5

.Lffn_p9_we5:
	v_and_b32_e32 v180, s28, v180
	v_and_b32_e32 v181, s28, v181
	v_lshlrev_b32_e32 v50, 16, v180
	v_and_b32_e32 v51, 0xffff0000, v180
	v_lshlrev_b32_e32 v52, 16, v181
	v_and_b32_e32 v53, 0xffff0000, v181
	v_lshlrev_b32_e32 v54, 16, v182
	v_and_b32_e32 v55, 0xffff0000, v182
	v_lshlrev_b32_e32 v56, 16, v183
	v_and_b32_e32 v57, 0xffff0000, v183
	v_lshlrev_b32_e32 v58, 16, v184
	v_and_b32_e32 v59, 0xffff0000, v184
	v_lshlrev_b32_e32 v60, 16, v185
	v_and_b32_e32 v61, 0xffff0000, v185
	v_lshlrev_b32_e32 v62, 16, v186
	v_and_b32_e32 v63, 0xffff0000, v186
	v_lshlrev_b32_e32 v64, 16, v187
	v_and_b32_e32 v65, 0xffff0000, v187
	v_lshlrev_b32_e32 v66, 16, v188
	v_and_b32_e32 v67, 0xffff0000, v188
	v_lshlrev_b32_e32 v68, 16, v189
	v_and_b32_e32 v69, 0xffff0000, v189
	v_and_b32_e32 v190, s29, v190
	v_and_b32_e32 v191, s29, v191
	v_lshlrev_b32_e32 v70, 16, v190
	v_and_b32_e32 v71, 0xffff0000, v190
	v_lshlrev_b32_e32 v72, 16, v191
	v_and_b32_e32 v73, 0xffff0000, v191
	v_and_b32_e32 v192, s42, v192
	v_and_b32_e32 v193, s42, v193
	v_and_b32_e32 v192, s28, v192
	v_and_b32_e32 v193, s28, v193
	v_lshlrev_b32_e32 v74, 16, v192
	v_and_b32_e32 v75, 0xffff0000, v192
	v_lshlrev_b32_e32 v76, 16, v193
	v_and_b32_e32 v77, 0xffff0000, v193
	v_and_b32_e32 v194, s42, v194
	v_and_b32_e32 v195, s42, v195
	v_lshlrev_b32_e32 v78, 16, v194
	v_and_b32_e32 v79, 0xffff0000, v194
	v_lshlrev_b32_e32 v80, 16, v195
	v_and_b32_e32 v81, 0xffff0000, v195
	v_and_b32_e32 v196, s42, v196
	v_and_b32_e32 v197, s42, v197
	v_lshlrev_b32_e32 v82, 16, v196
	v_and_b32_e32 v83, 0xffff0000, v196
	v_lshlrev_b32_e32 v84, 16, v197
	v_and_b32_e32 v85, 0xffff0000, v197
	v_and_b32_e32 v198, s42, v198
	v_and_b32_e32 v199, s42, v199
	v_lshlrev_b32_e32 v86, 16, v198
	v_and_b32_e32 v87, 0xffff0000, v198
	v_lshlrev_b32_e32 v88, 16, v199
	v_and_b32_e32 v89, 0xffff0000, v199
	v_and_b32_e32 v200, s42, v200
	v_and_b32_e32 v201, s42, v201
	v_lshlrev_b32_e32 v90, 16, v200
	v_and_b32_e32 v91, 0xffff0000, v200
	v_lshlrev_b32_e32 v92, 16, v201
	v_and_b32_e32 v93, 0xffff0000, v201
	v_and_b32_e32 v202, s42, v202
	v_and_b32_e32 v203, s42, v203
	v_and_b32_e32 v202, s29, v202
	v_and_b32_e32 v203, s29, v203
	v_lshlrev_b32_e32 v94, 16, v202
	v_and_b32_e32 v95, 0xffff0000, v202
	v_lshlrev_b32_e32 v96, 16, v203
	v_and_b32_e32 v97, 0xffff0000, v203
	s_cmp_eq_u32 s32, 7
	s_cbranch_scc1 .Lffn_p9_skipld8
	global_load_dword v180, v1, s[8:9]
	global_load_dword v181, v2, s[8:9]
	global_load_dword v182, v1, s[10:11]
	global_load_dword v183, v2, s[10:11]
	global_load_dword v184, v1, s[12:13]
	global_load_dword v185, v2, s[12:13]
	global_load_dword v186, v1, s[14:15]
	global_load_dword v187, v2, s[14:15]
	global_load_dword v188, v1, s[16:17]
	global_load_dword v189, v2, s[16:17]
	global_load_dword v190, v1, s[18:19]
	global_load_dword v191, v2, s[18:19]
	s_add_u32 s8, s8, 0x5800
	s_addc_u32 s9, s9, 0
	s_add_u32 s10, s10, 0x5800
	s_addc_u32 s11, s11, 0
	s_add_u32 s12, s12, 0x5800
	s_addc_u32 s13, s13, 0
	s_add_u32 s14, s14, 0x5800
	s_addc_u32 s15, s15, 0
	s_add_u32 s16, s16, 0x5800
	s_addc_u32 s17, s17, 0
	s_add_u32 s18, s18, 0x5800
	s_addc_u32 s19, s19, 0
	global_load_dword v192, v1, s[8:9]
	global_load_dword v193, v2, s[8:9]
	global_load_dword v194, v1, s[10:11]
	global_load_dword v195, v2, s[10:11]
	global_load_dword v196, v1, s[12:13]
	global_load_dword v197, v2, s[12:13]
	global_load_dword v198, v1, s[14:15]
	global_load_dword v199, v2, s[14:15]
	global_load_dword v200, v1, s[16:17]
	global_load_dword v201, v2, s[16:17]
	global_load_dword v202, v1, s[18:19]
	global_load_dword v203, v2, s[18:19]
	s_add_u32 s8, s8, 0x5800
	s_addc_u32 s9, s9, 0
	s_add_u32 s10, s10, 0x5800
	s_addc_u32 s11, s11, 0
	s_add_u32 s12, s12, 0x5800
	s_addc_u32 s13, s13, 0
	s_add_u32 s14, s14, 0x5800
	s_addc_u32 s15, s15, 0
	s_add_u32 s16, s16, 0x5800
	s_addc_u32 s17, s17, 0
	s_add_u32 s18, s18, 0x5800
	s_addc_u32 s19, s19, 0
.Lffn_p9_skipld8:
	v_pk_fma_f32 v[146:147], v[10:11], v[98:99], v[46:47]
	v_pk_fma_f32 v[148:149], v[28:29], v[100:101], v[48:49]
	v_pk_fma_f32 v[146:147], v[12:13], v[122:123], v[146:147]
	v_pk_fma_f32 v[148:149], v[30:31], v[124:125], v[148:149]
	v_pk_fma_f32 v[146:147], v[14:15], v[50:51], v[146:147]
	v_pk_fma_f32 v[148:149], v[32:33], v[52:53], v[148:149]
	v_pk_fma_f32 v[146:147], v[16:17], v[102:103], v[146:147]
	v_pk_fma_f32 v[148:149], v[34:35], v[104:105], v[148:149]
	v_pk_fma_f32 v[146:147], v[18:19], v[126:127], v[146:147]
	v_pk_fma_f32 v[148:149], v[36:37], v[128:129], v[148:149]
	v_pk_fma_f32 v[146:147], v[20:21], v[54:55], v[146:147]
	v_pk_fma_f32 v[148:149], v[38:39], v[56:57], v[148:149]
	v_pk_fma_f32 v[146:147], v[22:23], v[106:107], v[146:147]
	v_pk_fma_f32 v[148:149], v[40:41], v[108:109], v[148:149]
	v_pk_fma_f32 v[146:147], v[24:25], v[130:131], v[146:147]
	v_pk_fma_f32 v[148:149], v[42:43], v[132:133], v[148:149]
	v_pk_fma_f32 v[146:147], v[26:27], v[58:59], v[146:147]
	v_pk_fma_f32 v[148:149], v[44:45], v[60:61], v[148:149]
	v_pk_mul_f32 v[150:151], v[146:147], v[4:5]
	v_exp_f32_e32 v150, v150
	v_exp_f32_e32 v151, v151
	s_nop 0
	v_pk_add_f32 v[150:151], v[150:151], v[6:7]
	v_rcp_f32_e32 v150, v150
	v_rcp_f32_e32 v151, v151
	s_nop 0
	v_pk_mul_f32 v[150:151], v[150:151], v[146:147]
	v_pk_mul_f32 v[150:151], v[150:151], v[148:149]
	v_cvt_pk_bf16_f32 v204, v150, v151
	global_store_dword v1, v204, s[20:21]
	v_pk_fma_f32 v[146:147], v[10:11], v[102:103], v[46:47]
	v_pk_fma_f32 v[148:149], v[28:29], v[104:105], v[48:49]
	v_pk_fma_f32 v[146:147], v[12:13], v[126:127], v[146:147]
	v_pk_fma_f32 v[148:149], v[30:31], v[128:129], v[148:149]
	v_pk_fma_f32 v[146:147], v[14:15], v[54:55], v[146:147]
	v_pk_fma_f32 v[148:149], v[32:33], v[56:57], v[148:149]
	v_pk_fma_f32 v[146:147], v[16:17], v[106:107], v[146:147]
	v_pk_fma_f32 v[148:149], v[34:35], v[108:109], v[148:149]
	v_pk_fma_f32 v[146:147], v[18:19], v[130:131], v[146:147]
	v_pk_fma_f32 v[148:149], v[36:37], v[132:133], v[148:149]
	v_pk_fma_f32 v[146:147], v[20:21], v[58:59], v[146:147]
	v_pk_fma_f32 v[148:149], v[38:39], v[60:61], v[148:149]
	v_pk_fma_f32 v[146:147], v[22:23], v[110:111], v[146:147]
	v_pk_fma_f32 v[148:149], v[40:41], v[112:113], v[148:149]
	v_pk_fma_f32 v[146:147], v[24:25], v[134:135], v[146:147]
	v_pk_fma_f32 v[148:149], v[42:43], v[136:137], v[148:149]
	v_pk_fma_f32 v[146:147], v[26:27], v[62:63], v[146:147]
	v_pk_fma_f32 v[148:149], v[44:45], v[64:65], v[148:149]
	v_pk_mul_f32 v[150:151], v[146:147], v[4:5]
	v_exp_f32_e32 v150, v150
	v_exp_f32_e32 v151, v151
	s_nop 0
	v_pk_add_f32 v[150:151], v[150:151], v[6:7]
	v_rcp_f32_e32 v150, v150
	v_rcp_f32_e32 v151, v151
	s_nop 0
	v_pk_mul_f32 v[150:151], v[150:151], v[146:147]
	v_pk_mul_f32 v[150:151], v[150:151], v[148:149]
	v_cvt_pk_bf16_f32 v205, v150, v151
	global_store_dword v1, v205, s[22:23]
	v_pk_fma_f32 v[146:147], v[10:11], v[106:107], v[46:47]
	v_pk_fma_f32 v[148:149], v[28:29], v[108:109], v[48:49]
	v_pk_fma_f32 v[146:147], v[12:13], v[130:131], v[146:147]
	v_pk_fma_f32 v[148:149], v[30:31], v[132:133], v[148:149]
	v_pk_fma_f32 v[146:147], v[14:15], v[58:59], v[146:147]
	v_pk_fma_f32 v[148:149], v[32:33], v[60:61], v[148:149]
	v_pk_fma_f32 v[146:147], v[16:17], v[110:111], v[146:147]
	v_pk_fma_f32 v[148:149], v[34:35], v[112:113], v[148:149]
	v_pk_fma_f32 v[146:147], v[18:19], v[134:135], v[146:147]
	v_pk_fma_f32 v[148:149], v[36:37], v[136:137], v[148:149]
	v_pk_fma_f32 v[146:147], v[20:21], v[62:63], v[146:147]
	v_pk_fma_f32 v[148:149], v[38:39], v[64:65], v[148:149]
	v_pk_fma_f32 v[146:147], v[22:23], v[114:115], v[146:147]
	v_pk_fma_f32 v[148:149], v[40:41], v[116:117], v[148:149]
	v_pk_fma_f32 v[146:147], v[24:25], v[138:139], v[146:147]
	v_pk_fma_f32 v[148:149], v[42:43], v[140:141], v[148:149]
	v_pk_fma_f32 v[146:147], v[26:27], v[66:67], v[146:147]
	v_pk_fma_f32 v[148:149], v[44:45], v[68:69], v[148:149]
	v_pk_mul_f32 v[150:151], v[146:147], v[4:5]
	v_exp_f32_e32 v150, v150
	v_exp_f32_e32 v151, v151
	s_nop 0
	v_pk_add_f32 v[150:151], v[150:151], v[6:7]
	v_rcp_f32_e32 v150, v150
	v_rcp_f32_e32 v151, v151
	s_nop 0
	v_pk_mul_f32 v[150:151], v[150:151], v[146:147]
	v_pk_mul_f32 v[150:151], v[150:151], v[148:149]
	v_cvt_pk_bf16_f32 v206, v150, v151
	global_store_dword v1, v206, s[24:25]
	v_pk_fma_f32 v[146:147], v[10:11], v[110:111], v[46:47]
	v_pk_fma_f32 v[148:149], v[28:29], v[112:113], v[48:49]
	v_pk_fma_f32 v[146:147], v[12:13], v[134:135], v[146:147]
	v_pk_fma_f32 v[148:149], v[30:31], v[136:137], v[148:149]
	v_pk_fma_f32 v[146:147], v[14:15], v[62:63], v[146:147]
	v_pk_fma_f32 v[148:149], v[32:33], v[64:65], v[148:149]
	v_pk_fma_f32 v[146:147], v[16:17], v[114:115], v[146:147]
	v_pk_fma_f32 v[148:149], v[34:35], v[116:117], v[148:149]
	v_pk_fma_f32 v[146:147], v[18:19], v[138:139], v[146:147]
	v_pk_fma_f32 v[148:149], v[36:37], v[140:141], v[148:149]
	v_pk_fma_f32 v[146:147], v[20:21], v[66:67], v[146:147]
	v_pk_fma_f32 v[148:149], v[38:39], v[68:69], v[148:149]
	v_pk_fma_f32 v[146:147], v[22:23], v[118:119], v[146:147]
	v_pk_fma_f32 v[148:149], v[40:41], v[120:121], v[148:149]
	v_pk_fma_f32 v[146:147], v[24:25], v[142:143], v[146:147]
	v_pk_fma_f32 v[148:149], v[42:43], v[144:145], v[148:149]
	v_pk_fma_f32 v[146:147], v[26:27], v[70:71], v[146:147]
	v_pk_fma_f32 v[148:149], v[44:45], v[72:73], v[148:149]
	v_pk_mul_f32 v[150:151], v[146:147], v[4:5]
	v_exp_f32_e32 v150, v150
	v_exp_f32_e32 v151, v151
	s_nop 0
	v_pk_add_f32 v[150:151], v[150:151], v[6:7]
	v_rcp_f32_e32 v150, v150
	v_rcp_f32_e32 v151, v151
	s_nop 0
	v_pk_mul_f32 v[150:151], v[150:151], v[146:147]
	v_pk_mul_f32 v[150:151], v[150:151], v[148:149]
	v_cvt_pk_bf16_f32 v207, v150, v151
	global_store_dword v1, v207, s[26:27]
	s_add_u32 s20, s20, 0x2c00
	s_addc_u32 s21, s21, 0
	s_add_u32 s22, s22, 0x2c00
	s_addc_u32 s23, s23, 0
	s_add_u32 s24, s24, 0x2c00
	s_addc_u32 s25, s25, 0
	s_add_u32 s26, s26, 0x2c00
	s_addc_u32 s27, s27, 0
	v_pk_fma_f32 v[146:147], v[10:11], v[122:123], v[46:47]
	v_pk_fma_f32 v[148:149], v[28:29], v[124:125], v[48:49]
	v_pk_fma_f32 v[146:147], v[12:13], v[50:51], v[146:147]
	v_pk_fma_f32 v[148:149], v[30:31], v[52:53], v[148:149]
	v_pk_fma_f32 v[146:147], v[14:15], v[74:75], v[146:147]
	v_pk_fma_f32 v[148:149], v[32:33], v[76:77], v[148:149]
	v_pk_fma_f32 v[146:147], v[16:17], v[126:127], v[146:147]
	v_pk_fma_f32 v[148:149], v[34:35], v[128:129], v[148:149]
	v_pk_fma_f32 v[146:147], v[18:19], v[54:55], v[146:147]
	v_pk_fma_f32 v[148:149], v[36:37], v[56:57], v[148:149]
	v_pk_fma_f32 v[146:147], v[20:21], v[78:79], v[146:147]
	v_pk_fma_f32 v[148:149], v[38:39], v[80:81], v[148:149]
	v_pk_fma_f32 v[146:147], v[22:23], v[130:131], v[146:147]
	v_pk_fma_f32 v[148:149], v[40:41], v[132:133], v[148:149]
	v_pk_fma_f32 v[146:147], v[24:25], v[58:59], v[146:147]
	v_pk_fma_f32 v[148:149], v[42:43], v[60:61], v[148:149]
	v_pk_fma_f32 v[146:147], v[26:27], v[82:83], v[146:147]
	v_pk_fma_f32 v[148:149], v[44:45], v[84:85], v[148:149]
	v_pk_mul_f32 v[150:151], v[146:147], v[4:5]
	v_exp_f32_e32 v150, v150
	v_exp_f32_e32 v151, v151
	s_nop 0
	v_pk_add_f32 v[150:151], v[150:151], v[6:7]
	v_rcp_f32_e32 v150, v150
	v_rcp_f32_e32 v151, v151
	s_nop 0
	v_pk_mul_f32 v[150:151], v[150:151], v[146:147]
	v_pk_mul_f32 v[150:151], v[150:151], v[148:149]
	v_cvt_pk_bf16_f32 v204, v150, v151
	global_store_dword v1, v204, s[20:21]
	v_pk_fma_f32 v[146:147], v[10:11], v[126:127], v[46:47]
	v_pk_fma_f32 v[148:149], v[28:29], v[128:129], v[48:49]
	v_pk_fma_f32 v[146:147], v[12:13], v[54:55], v[146:147]
	v_pk_fma_f32 v[148:149], v[30:31], v[56:57], v[148:149]
	v_pk_fma_f32 v[146:147], v[14:15], v[78:79], v[146:147]
	v_pk_fma_f32 v[148:149], v[32:33], v[80:81], v[148:149]
	v_pk_fma_f32 v[146:147], v[16:17], v[130:131], v[146:147]
	v_pk_fma_f32 v[148:149], v[34:35], v[132:133], v[148:149]
	v_pk_fma_f32 v[146:147], v[18:19], v[58:59], v[146:147]
	v_pk_fma_f32 v[148:149], v[36:37], v[60:61], v[148:149]
	v_pk_fma_f32 v[146:147], v[20:21], v[82:83], v[146:147]
	v_pk_fma_f32 v[148:149], v[38:39], v[84:85], v[148:149]
	v_pk_fma_f32 v[146:147], v[22:23], v[134:135], v[146:147]
	v_pk_fma_f32 v[148:149], v[40:41], v[136:137], v[148:149]
	v_pk_fma_f32 v[146:147], v[24:25], v[62:63], v[146:147]
	v_pk_fma_f32 v[148:149], v[42:43], v[64:65], v[148:149]
	v_pk_fma_f32 v[146:147], v[26:27], v[86:87], v[146:147]
	v_pk_fma_f32 v[148:149], v[44:45], v[88:89], v[148:149]
	v_pk_mul_f32 v[150:151], v[146:147], v[4:5]
	v_exp_f32_e32 v150, v150
	v_exp_f32_e32 v151, v151
	s_nop 0
	v_pk_add_f32 v[150:151], v[150:151], v[6:7]
	v_rcp_f32_e32 v150, v150
	v_rcp_f32_e32 v151, v151
	s_nop 0
	v_pk_mul_f32 v[150:151], v[150:151], v[146:147]
	v_pk_mul_f32 v[150:151], v[150:151], v[148:149]
	v_cvt_pk_bf16_f32 v205, v150, v151
	global_store_dword v1, v205, s[22:23]
	v_pk_fma_f32 v[146:147], v[10:11], v[130:131], v[46:47]
	v_pk_fma_f32 v[148:149], v[28:29], v[132:133], v[48:49]
	v_pk_fma_f32 v[146:147], v[12:13], v[58:59], v[146:147]
	v_pk_fma_f32 v[148:149], v[30:31], v[60:61], v[148:149]
	v_pk_fma_f32 v[146:147], v[14:15], v[82:83], v[146:147]
	v_pk_fma_f32 v[148:149], v[32:33], v[84:85], v[148:149]
	v_pk_fma_f32 v[146:147], v[16:17], v[134:135], v[146:147]
	v_pk_fma_f32 v[148:149], v[34:35], v[136:137], v[148:149]
	v_pk_fma_f32 v[146:147], v[18:19], v[62:63], v[146:147]
	v_pk_fma_f32 v[148:149], v[36:37], v[64:65], v[148:149]
	v_pk_fma_f32 v[146:147], v[20:21], v[86:87], v[146:147]
	v_pk_fma_f32 v[148:149], v[38:39], v[88:89], v[148:149]
	v_pk_fma_f32 v[146:147], v[22:23], v[138:139], v[146:147]
	v_pk_fma_f32 v[148:149], v[40:41], v[140:141], v[148:149]
	v_pk_fma_f32 v[146:147], v[24:25], v[66:67], v[146:147]
	v_pk_fma_f32 v[148:149], v[42:43], v[68:69], v[148:149]
	v_pk_fma_f32 v[146:147], v[26:27], v[90:91], v[146:147]
	v_pk_fma_f32 v[148:149], v[44:45], v[92:93], v[148:149]
	v_pk_mul_f32 v[150:151], v[146:147], v[4:5]
	v_exp_f32_e32 v150, v150
	v_exp_f32_e32 v151, v151
	s_nop 0
	v_pk_add_f32 v[150:151], v[150:151], v[6:7]
	v_rcp_f32_e32 v150, v150
	v_rcp_f32_e32 v151, v151
	s_nop 0
	v_pk_mul_f32 v[150:151], v[150:151], v[146:147]
	v_pk_mul_f32 v[150:151], v[150:151], v[148:149]
	v_cvt_pk_bf16_f32 v206, v150, v151
	global_store_dword v1, v206, s[24:25]
	v_pk_fma_f32 v[146:147], v[10:11], v[134:135], v[46:47]
	v_pk_fma_f32 v[148:149], v[28:29], v[136:137], v[48:49]
	v_pk_fma_f32 v[146:147], v[12:13], v[62:63], v[146:147]
	v_pk_fma_f32 v[148:149], v[30:31], v[64:65], v[148:149]
	v_pk_fma_f32 v[146:147], v[14:15], v[86:87], v[146:147]
	v_pk_fma_f32 v[148:149], v[32:33], v[88:89], v[148:149]
	v_pk_fma_f32 v[146:147], v[16:17], v[138:139], v[146:147]
	v_pk_fma_f32 v[148:149], v[34:35], v[140:141], v[148:149]
	v_pk_fma_f32 v[146:147], v[18:19], v[66:67], v[146:147]
	v_pk_fma_f32 v[148:149], v[36:37], v[68:69], v[148:149]
	v_pk_fma_f32 v[146:147], v[20:21], v[90:91], v[146:147]
	v_pk_fma_f32 v[148:149], v[38:39], v[92:93], v[148:149]
	v_pk_fma_f32 v[146:147], v[22:23], v[142:143], v[146:147]
	v_pk_fma_f32 v[148:149], v[40:41], v[144:145], v[148:149]
	v_pk_fma_f32 v[146:147], v[24:25], v[70:71], v[146:147]
	v_pk_fma_f32 v[148:149], v[42:43], v[72:73], v[148:149]
	v_pk_fma_f32 v[146:147], v[26:27], v[94:95], v[146:147]
	v_pk_fma_f32 v[148:149], v[44:45], v[96:97], v[148:149]
	v_pk_mul_f32 v[150:151], v[146:147], v[4:5]
	v_exp_f32_e32 v150, v150
	v_exp_f32_e32 v151, v151
	s_nop 0
	v_pk_add_f32 v[150:151], v[150:151], v[6:7]
	v_rcp_f32_e32 v150, v150
	v_rcp_f32_e32 v151, v151
	s_nop 0
	v_pk_mul_f32 v[150:151], v[150:151], v[146:147]
	v_pk_mul_f32 v[150:151], v[150:151], v[148:149]
	v_cvt_pk_bf16_f32 v207, v150, v151
	global_store_dword v1, v207, s[26:27]
	s_add_u32 s20, s20, 0x2c00
	s_addc_u32 s21, s21, 0
	s_add_u32 s22, s22, 0x2c00
	s_addc_u32 s23, s23, 0
	s_add_u32 s24, s24, 0x2c00
	s_addc_u32 s25, s25, 0
	s_add_u32 s26, s26, 0x2c00
	s_addc_u32 s27, s27, 0
	s_add_u32 s32, s32, 1
	s_cmp_lt_u32 s32, 8
	s_cbranch_scc1 .Lffn_p9_loop_lat1
	s_branch .Lffn_p9_itemend
.Lffn_p9_ctx:
	s_sub_u32 s35, s6, 1408
	s_mul_i32 s33, s35, 47663
	s_lshr_b32 s33, s33, 21
	s_mul_i32 s34, s33, 44
	s_sub_u32 s43, s35, s34
	s_and_b32 s34, s33, 3
	s_lshr_b32 s36, s33, 2
	s_mov_b32 s28, -1
	s_mov_b32 s29, -1
	s_cmp_lg_u32 s34, 0
	s_cselect_b32 s30, -1, 0
	s_cmp_lg_u32 s34, 3
	s_cselect_b32 s31, -1, 0
	s_lshl_b32 s36, s36, 8
	s_lshl_b32 s34, s34, 6
	s_add_u32 s36, s36, s34
	v_and_b32_e32 v1, 63, v154
	v_lshlrev_b32_e32 v1, 2, v1
	s_lshl_b32 s33, s43, 8
	v_add_u32_e32 v1, s33, v1
	v_add_u32_e32 v2, 0x2c00, v1
	v_lshlrev_b32_e32 v3, 1, v1
	s_add_i32 s33, s36, 0
	s_mul_i32 s33, s33, 0x2c00
	s_add_u32 s20, s40, s33
	s_addc_u32 s21, s41, 0
	s_add_i32 s33, s36, -1
	s_mul_i32 s33, s33, 0x5800
	s_ashr_i32 s34, s33, 31
	s_add_u32 s8, s38, s33
	s_addc_u32 s9, s39, s34
	s_add_u32 s33, s0, 0x0
	s_addc_u32 s34, s1, 0
	s_mov_b32 s36, s33
	s_mov_b32 s37, s34
	global_load_dwordx2 v[10:11], v3, s[36:37]
	s_add_u32 s36, s36, 0x5800
	s_addc_u32 s37, s37, 0
	global_load_dwordx2 v[28:29], v3, s[36:37]
	s_add_u32 s33, s0, 0xb000
	s_addc_u32 s34, s1, 0
	s_mov_b32 s36, s33
	s_mov_b32 s37, s34
	global_load_dwordx2 v[12:13], v3, s[36:37]
	s_add_u32 s36, s36, 0x5800
	s_addc_u32 s37, s37, 0
	global_load_dwordx2 v[30:31], v3, s[36:37]
	s_add_u32 s33, s0, 0x16000
	s_addc_u32 s34, s1, 0
	s_mov_b32 s36, s33
	s_mov_b32 s37, s34
	global_load_dwordx2 v[14:15], v3, s[36:37]
	s_add_u32 s36, s36, 0x5800
	s_addc_u32 s37, s37, 0
	global_load_dwordx2 v[32:33], v3, s[36:37]
	s_add_u32 s33, s0, 0x21000
	s_addc_u32 s34, s1, 0
	s_mov_b32 s36, s33
	s_mov_b32 s37, s34
	global_load_dwordx2 v[16:17], v3, s[36:37]
	s_add_u32 s36, s36, 0x5800
	s_addc_u32 s37, s37, 0
	global_load_dwordx2 v[34:35], v3, s[36:37]
	s_add_u32 s33, s0, 0x2c000
	s_addc_u32 s34, s1, 0
	s_mov_b32 s36, s33
	s_mov_b32 s37, s34
	global_load_dwordx2 v[18:19], v3, s[36:37]
	s_add_u32 s36, s36, 0x5800
	s_addc_u32 s37, s37, 0
	global_load_dwordx2 v[36:37], v3, s[36:37]
	s_add_u32 s33, s0, 0x37000
	s_addc_u32 s34, s1, 0
	s_mov_b32 s36, s33
	s_mov_b32 s37, s34
	global_load_dwordx2 v[20:21], v3, s[36:37]
	s_add_u32 s36, s36, 0x5800
	s_addc_u32 s37, s37, 0
	global_load_dwordx2 v[38:39], v3, s[36:37]
	s_add_u32 s33, s0, 0x42000
	s_addc_u32 s34, s1, 0
	s_mov_b32 s36, s33
	s_mov_b32 s37, s34
	global_load_dwordx2 v[22:23], v3, s[36:37]
	s_add_u32 s36, s36, 0x5800
	s_addc_u32 s37, s37, 0
	global_load_dwordx2 v[40:41], v3, s[36:37]
	s_add_u32 s33, s0, 0x4d000
	s_addc_u32 s34, s1, 0
	s_mov_b32 s36, s33
	s_mov_b32 s37, s34
	global_load_dwordx2 v[24:25], v3, s[36:37]
	s_add_u32 s36, s36, 0x5800
	s_addc_u32 s37, s37, 0
	global_load_dwordx2 v[42:43], v3, s[36:37]
	s_add_u32 s33, s0, 0x58000
	s_addc_u32 s34, s1, 0
	s_mov_b32 s36, s33
	s_mov_b32 s37, s34
	global_load_dwordx2 v[26:27], v3, s[36:37]
	s_add_u32 s36, s36, 0x5800
	s_addc_u32 s37, s37, 0
	global_load_dwordx2 v[44:45], v3, s[36:37]
	global_load_dwordx2 v[46:47], v3, s[2:3]
	s_add_u32 s36, s2, 0x5800
	s_addc_u32 s37, s3, 0
	global_load_dwordx2 v[48:49], v3, s[36:37]
	global_load_dword v172, v1, s[8:9]
	global_load_dword v173, v2, s[8:9]
	s_add_u32 s8, s8, 0x5800
	s_addc_u32 s9, s9, 0
	global_load_dword v174, v1, s[8:9]
	global_load_dword v175, v2, s[8:9]
	s_add_u32 s8, s8, 0x5800
	s_addc_u32 s9, s9, 0
	global_load_dword v156, v1, s[8:9]
	global_load_dword v157, v2, s[8:9]
	s_add_u32 s8, s8, 0x5800
	s_addc_u32 s9, s9, 0
	global_load_dword v158, v1, s[8:9]
	global_load_dword v159, v2, s[8:9]
	s_add_u32 s8, s8, 0x5800
	s_addc_u32 s9, s9, 0
	global_load_dword v160, v1, s[8:9]
	global_load_dword v161, v2, s[8:9]
	s_add_u32 s8, s8, 0x5800
	s_addc_u32 s9, s9, 0
	global_load_dword v162, v1, s[8:9]
	global_load_dword v163, v2, s[8:9]
	s_add_u32 s8, s8, 0x5800
	s_addc_u32 s9, s9, 0
	global_load_dword v164, v1, s[8:9]
	global_load_dword v165, v2, s[8:9]
	s_add_u32 s8, s8, 0x5800
	s_addc_u32 s9, s9, 0
	global_load_dword v166, v1, s[8:9]
	global_load_dword v167, v2, s[8:9]
	s_add_u32 s8, s8, 0x5800
	s_addc_u32 s9, s9, 0
	global_load_dword v168, v1, s[8:9]
	global_load_dword v169, v2, s[8:9]
	s_add_u32 s8, s8, 0x5800
	s_addc_u32 s9, s9, 0
	global_load_dword v170, v1, s[8:9]
	global_load_dword v171, v2, s[8:9]
	s_add_u32 s8, s8, 0x5800
	s_addc_u32 s9, s9, 0
	s_waitcnt vmcnt(16)
	v_and_b32_e32 v172, s30, v172
	v_and_b32_e32 v173, s30, v173
	v_lshlrev_b32_e32 v82, 16, v172
	v_and_b32_e32 v83, 0xffff0000, v172
	v_lshlrev_b32_e32 v84, 16, v173
	v_and_b32_e32 v85, 0xffff0000, v173
	v_lshlrev_b32_e32 v86, 16, v174
	v_and_b32_e32 v87, 0xffff0000, v174
	v_lshlrev_b32_e32 v88, 16, v175
	v_and_b32_e32 v89, 0xffff0000, v175
	global_load_dword v172, v1, s[8:9]
	global_load_dword v173, v2, s[8:9]
	s_add_u32 s8, s8, 0x5800
	s_addc_u32 s9, s9, 0
	global_load_dword v174, v1, s[8:9]
	global_load_dword v175, v2, s[8:9]
	s_add_u32 s8, s8, 0x5800
	s_addc_u32 s9, s9, 0
	global_load_dword v176, v1, s[8:9]
	global_load_dword v177, v2, s[8:9]
	s_add_u32 s8, s8, 0x5800
	s_addc_u32 s9, s9, 0
	global_load_dword v178, v1, s[8:9]
	global_load_dword v179, v2, s[8:9]
	s_add_u32 s8, s8, 0x5800
	s_addc_u32 s9, s9, 0
	global_load_dword v180, v1, s[8:9]
	global_load_dword v181, v2, s[8:9]
	s_add_u32 s8, s8, 0x5800
	s_addc_u32 s9, s9, 0
	global_load_dword v182, v1, s[8:9]
	global_load_dword v183, v2, s[8:9]
	s_add_u32 s8, s8, 0x5800
	s_addc_u32 s9, s9, 0
	global_load_dword v184, v1, s[8:9]
	global_load_dword v185, v2, s[8:9]
	s_add_u32 s8, s8, 0x5800
	s_addc_u32 s9, s9, 0
	global_load_dword v186, v1, s[8:9]
	global_load_dword v187, v2, s[8:9]
	s_add_u32 s8, s8, 0x5800
	s_addc_u32 s9, s9, 0
	s_mov_b32 s32, 0
.Lffn_p9_loop_ctx9:
	s_cmp_eq_u32 s32, 3
	s_cselect_b32 s42, s31, -1
	s_cmp_lg_u32 s32, 0
	s_cbranch_scc1 .Lffn_p9_wn11
	s_waitcnt vmcnt(16)
	s_branch .Lffn_p9_we10

.Lffn_p9_we10:
	v_mov_b32_e32 v50, v82
	v_mov_b32_e32 v51, v83
	v_mov_b32_e32 v52, v84
	v_mov_b32_e32 v53, v85
	v_mov_b32_e32 v54, v86
	v_mov_b32_e32 v55, v87
	v_mov_b32_e32 v56, v88
	v_mov_b32_e32 v57, v89
	v_lshlrev_b32_e32 v58, 16, v156
	v_and_b32_e32 v59, 0xffff0000, v156
	v_lshlrev_b32_e32 v60, 16, v157
	v_and_b32_e32 v61, 0xffff0000, v157
	v_lshlrev_b32_e32 v62, 16, v158
	v_and_b32_e32 v63, 0xffff0000, v158
	v_lshlrev_b32_e32 v64, 16, v159
	v_and_b32_e32 v65, 0xffff0000, v159
	v_lshlrev_b32_e32 v66, 16, v160
	v_and_b32_e32 v67, 0xffff0000, v160
	v_lshlrev_b32_e32 v68, 16, v161
	v_and_b32_e32 v69, 0xffff0000, v161
	v_lshlrev_b32_e32 v70, 16, v162
	v_and_b32_e32 v71, 0xffff0000, v162
	v_lshlrev_b32_e32 v72, 16, v163
	v_and_b32_e32 v73, 0xffff0000, v163
	v_lshlrev_b32_e32 v74, 16, v164
	v_and_b32_e32 v75, 0xffff0000, v164
	v_lshlrev_b32_e32 v76, 16, v165
	v_and_b32_e32 v77, 0xffff0000, v165
	v_lshlrev_b32_e32 v78, 16, v166
	v_and_b32_e32 v79, 0xffff0000, v166
	v_lshlrev_b32_e32 v80, 16, v167
	v_and_b32_e32 v81, 0xffff0000, v167
	v_lshlrev_b32_e32 v82, 16, v168
	v_and_b32_e32 v83, 0xffff0000, v168
	v_lshlrev_b32_e32 v84, 16, v169
	v_and_b32_e32 v85, 0xffff0000, v169
	v_lshlrev_b32_e32 v86, 16, v170
	v_and_b32_e32 v87, 0xffff0000, v170
	v_lshlrev_b32_e32 v88, 16, v171
	v_and_b32_e32 v89, 0xffff0000, v171
	s_cmp_eq_u32 s32, 3
	s_cbranch_scc1 .Lffn_p9_skipld12
	global_load_dword v156, v1, s[8:9]
	global_load_dword v157, v2, s[8:9]
	s_add_u32 s8, s8, 0x5800
	s_addc_u32 s9, s9, 0
	global_load_dword v158, v1, s[8:9]
	global_load_dword v159, v2, s[8:9]
	s_add_u32 s8, s8, 0x5800
	s_addc_u32 s9, s9, 0
	global_load_dword v160, v1, s[8:9]
	global_load_dword v161, v2, s[8:9]
	s_add_u32 s8, s8, 0x5800
	s_addc_u32 s9, s9, 0
	global_load_dword v162, v1, s[8:9]
	global_load_dword v163, v2, s[8:9]
	s_add_u32 s8, s8, 0x5800
	s_addc_u32 s9, s9, 0
	global_load_dword v164, v1, s[8:9]
	global_load_dword v165, v2, s[8:9]
	s_add_u32 s8, s8, 0x5800
	s_addc_u32 s9, s9, 0
	global_load_dword v166, v1, s[8:9]
	global_load_dword v167, v2, s[8:9]
	s_add_u32 s8, s8, 0x5800
	s_addc_u32 s9, s9, 0
	global_load_dword v168, v1, s[8:9]
	global_load_dword v169, v2, s[8:9]
	s_add_u32 s8, s8, 0x5800
	s_addc_u32 s9, s9, 0
	global_load_dword v170, v1, s[8:9]
	global_load_dword v171, v2, s[8:9]
	s_add_u32 s8, s8, 0x5800
	s_addc_u32 s9, s9, 0
.Lffn_p9_skipld12:
	v_pk_fma_f32 v[146:147], v[16:17], v[50:51], v[46:47]
	v_pk_fma_f32 v[148:149], v[34:35], v[52:53], v[48:49]
	v_pk_fma_f32 v[146:147], v[18:19], v[54:55], v[146:147]
	v_pk_fma_f32 v[148:149], v[36:37], v[56:57], v[148:149]
	v_pk_fma_f32 v[146:147], v[20:21], v[58:59], v[146:147]
	v_pk_fma_f32 v[148:149], v[38:39], v[60:61], v[148:149]
	v_pk_mul_f32 v[150:151], v[146:147], v[4:5]
	v_exp_f32_e32 v150, v150
	v_exp_f32_e32 v151, v151
	s_nop 0
	v_pk_add_f32 v[150:151], v[150:151], v[6:7]
	v_rcp_f32_e32 v150, v150
	v_rcp_f32_e32 v151, v151
	s_nop 0
	v_pk_mul_f32 v[150:151], v[150:151], v[146:147]
	v_pk_mul_f32 v[150:151], v[150:151], v[148:149]
	v_cvt_pk_bf16_f32 v204, v150, v151
	global_store_dword v1, v204, s[20:21]
	s_add_u32 s20, s20, 0x2c00
	s_addc_u32 s21, s21, 0
	v_pk_fma_f32 v[146:147], v[16:17], v[54:55], v[46:47]
	v_pk_fma_f32 v[148:149], v[34:35], v[56:57], v[48:49]
	v_pk_fma_f32 v[146:147], v[18:19], v[58:59], v[146:147]
	v_pk_fma_f32 v[148:149], v[36:37], v[60:61], v[148:149]
	v_pk_fma_f32 v[146:147], v[20:21], v[62:63], v[146:147]
	v_pk_fma_f32 v[148:149], v[38:39], v[64:65], v[148:149]
	v_pk_mul_f32 v[150:151], v[146:147], v[4:5]
	v_exp_f32_e32 v150, v150
	v_exp_f32_e32 v151, v151
	s_nop 0
	v_pk_add_f32 v[150:151], v[150:151], v[6:7]
	v_rcp_f32_e32 v150, v150
	v_rcp_f32_e32 v151, v151
	s_nop 0
	v_pk_mul_f32 v[150:151], v[150:151], v[146:147]
	v_pk_mul_f32 v[150:151], v[150:151], v[148:149]
	v_cvt_pk_bf16_f32 v205, v150, v151
	global_store_dword v1, v205, s[20:21]
	s_add_u32 s20, s20, 0x2c00
	s_addc_u32 s21, s21, 0
	v_pk_fma_f32 v[146:147], v[16:17], v[58:59], v[46:47]
	v_pk_fma_f32 v[148:149], v[34:35], v[60:61], v[48:49]
	v_pk_fma_f32 v[146:147], v[18:19], v[62:63], v[146:147]
	v_pk_fma_f32 v[148:149], v[36:37], v[64:65], v[148:149]
	v_pk_fma_f32 v[146:147], v[20:21], v[66:67], v[146:147]
	v_pk_fma_f32 v[148:149], v[38:39], v[68:69], v[148:149]
	v_pk_mul_f32 v[150:151], v[146:147], v[4:5]
	v_exp_f32_e32 v150, v150
	v_exp_f32_e32 v151, v151
	s_nop 0
	v_pk_add_f32 v[150:151], v[150:151], v[6:7]
	v_rcp_f32_e32 v150, v150
	v_rcp_f32_e32 v151, v151
	s_nop 0
	v_pk_mul_f32 v[150:151], v[150:151], v[146:147]
	v_pk_mul_f32 v[150:151], v[150:151], v[148:149]
	v_cvt_pk_bf16_f32 v206, v150, v151
	global_store_dword v1, v206, s[20:21]
	s_add_u32 s20, s20, 0x2c00
	s_addc_u32 s21, s21, 0
	v_pk_fma_f32 v[146:147], v[16:17], v[62:63], v[46:47]
	v_pk_fma_f32 v[148:149], v[34:35], v[64:65], v[48:49]
	v_pk_fma_f32 v[146:147], v[18:19], v[66:67], v[146:147]
	v_pk_fma_f32 v[148:149], v[36:37], v[68:69], v[148:149]
	v_pk_fma_f32 v[146:147], v[20:21], v[70:71], v[146:147]
	v_pk_fma_f32 v[148:149], v[38:39], v[72:73], v[148:149]
	v_pk_mul_f32 v[150:151], v[146:147], v[4:5]
	v_exp_f32_e32 v150, v150
	v_exp_f32_e32 v151, v151
	s_nop 0
	v_pk_add_f32 v[150:151], v[150:151], v[6:7]
	v_rcp_f32_e32 v150, v150
	v_rcp_f32_e32 v151, v151
	s_nop 0
	v_pk_mul_f32 v[150:151], v[150:151], v[146:147]
	v_pk_mul_f32 v[150:151], v[150:151], v[148:149]
	v_cvt_pk_bf16_f32 v207, v150, v151
	global_store_dword v1, v207, s[20:21]
	s_add_u32 s20, s20, 0x2c00
	s_addc_u32 s21, s21, 0
	v_pk_fma_f32 v[146:147], v[16:17], v[66:67], v[46:47]
	v_pk_fma_f32 v[148:149], v[34:35], v[68:69], v[48:49]
	v_pk_fma_f32 v[146:147], v[18:19], v[70:71], v[146:147]
	v_pk_fma_f32 v[148:149], v[36:37], v[72:73], v[148:149]
	v_pk_fma_f32 v[146:147], v[20:21], v[74:75], v[146:147]
	v_pk_fma_f32 v[148:149], v[38:39], v[76:77], v[148:149]
	v_pk_mul_f32 v[150:151], v[146:147], v[4:5]
	v_exp_f32_e32 v150, v150
	v_exp_f32_e32 v151, v151
	s_nop 0
	v_pk_add_f32 v[150:151], v[150:151], v[6:7]
	v_rcp_f32_e32 v150, v150
	v_rcp_f32_e32 v151, v151
	s_nop 0
	v_pk_mul_f32 v[150:151], v[150:151], v[146:147]
	v_pk_mul_f32 v[150:151], v[150:151], v[148:149]
	v_cvt_pk_bf16_f32 v204, v150, v151
	global_store_dword v1, v204, s[20:21]
	s_add_u32 s20, s20, 0x2c00
	s_addc_u32 s21, s21, 0
	v_pk_fma_f32 v[146:147], v[16:17], v[70:71], v[46:47]
	v_pk_fma_f32 v[148:149], v[34:35], v[72:73], v[48:49]
	v_pk_fma_f32 v[146:147], v[18:19], v[74:75], v[146:147]
	v_pk_fma_f32 v[148:149], v[36:37], v[76:77], v[148:149]
	v_pk_fma_f32 v[146:147], v[20:21], v[78:79], v[146:147]
	v_pk_fma_f32 v[148:149], v[38:39], v[80:81], v[148:149]
	v_pk_mul_f32 v[150:151], v[146:147], v[4:5]
	v_exp_f32_e32 v150, v150
	v_exp_f32_e32 v151, v151
	s_nop 0
	v_pk_add_f32 v[150:151], v[150:151], v[6:7]
	v_rcp_f32_e32 v150, v150
	v_rcp_f32_e32 v151, v151
	s_nop 0
	v_pk_mul_f32 v[150:151], v[150:151], v[146:147]
	v_pk_mul_f32 v[150:151], v[150:151], v[148:149]
	v_cvt_pk_bf16_f32 v205, v150, v151
	global_store_dword v1, v205, s[20:21]
	s_add_u32 s20, s20, 0x2c00
	s_addc_u32 s21, s21, 0
	v_pk_fma_f32 v[146:147], v[16:17], v[74:75], v[46:47]
	v_pk_fma_f32 v[148:149], v[34:35], v[76:77], v[48:49]
	v_pk_fma_f32 v[146:147], v[18:19], v[78:79], v[146:147]
	v_pk_fma_f32 v[148:149], v[36:37], v[80:81], v[148:149]
	v_pk_fma_f32 v[146:147], v[20:21], v[82:83], v[146:147]
	v_pk_fma_f32 v[148:149], v[38:39], v[84:85], v[148:149]
	v_pk_mul_f32 v[150:151], v[146:147], v[4:5]
	v_exp_f32_e32 v150, v150
	v_exp_f32_e32 v151, v151
	s_nop 0
	v_pk_add_f32 v[150:151], v[150:151], v[6:7]
	v_rcp_f32_e32 v150, v150
	v_rcp_f32_e32 v151, v151
	s_nop 0
	v_pk_mul_f32 v[150:151], v[150:151], v[146:147]
	v_pk_mul_f32 v[150:151], v[150:151], v[148:149]
	v_cvt_pk_bf16_f32 v206, v150, v151
	global_store_dword v1, v206, s[20:21]
	s_add_u32 s20, s20, 0x2c00
	s_addc_u32 s21, s21, 0
	v_pk_fma_f32 v[146:147], v[16:17], v[78:79], v[46:47]
	v_pk_fma_f32 v[148:149], v[34:35], v[80:81], v[48:49]
	v_pk_fma_f32 v[146:147], v[18:19], v[82:83], v[146:147]
	v_pk_fma_f32 v[148:149], v[36:37], v[84:85], v[148:149]
	v_pk_fma_f32 v[146:147], v[20:21], v[86:87], v[146:147]
	v_pk_fma_f32 v[148:149], v[38:39], v[88:89], v[148:149]
	v_pk_mul_f32 v[150:151], v[146:147], v[4:5]
	v_exp_f32_e32 v150, v150
	v_exp_f32_e32 v151, v151
	s_nop 0
	v_pk_add_f32 v[150:151], v[150:151], v[6:7]
	v_rcp_f32_e32 v150, v150
	v_rcp_f32_e32 v151, v151
	s_nop 0
	v_pk_mul_f32 v[150:151], v[150:151], v[146:147]
	v_pk_mul_f32 v[150:151], v[150:151], v[148:149]
	v_cvt_pk_bf16_f32 v207, v150, v151
	global_store_dword v1, v207, s[20:21]
	s_add_u32 s20, s20, 0x2c00
	s_addc_u32 s21, s21, 0
	s_cmp_lg_u32 s32, 0
	s_cbranch_scc1 .Lffn_p9_wn14
	s_waitcnt vmcnt(24)
	s_branch .Lffn_p9_we13
.Lffn_p9_wn14:
	s_cmp_lg_u32 s32, 3
	s_cbranch_scc1 .Lffn_p9_wn15
	s_waitcnt vmcnt(16)
	s_branch .Lffn_p9_we13

.Lffn_p9_we13:
	v_mov_b32_e32 v50, v82
	v_mov_b32_e32 v51, v83
	v_mov_b32_e32 v52, v84
	v_mov_b32_e32 v53, v85
	v_mov_b32_e32 v54, v86
	v_mov_b32_e32 v55, v87
	v_mov_b32_e32 v56, v88
	v_mov_b32_e32 v57, v89
	v_lshlrev_b32_e32 v58, 16, v172
	v_and_b32_e32 v59, 0xffff0000, v172
	v_lshlrev_b32_e32 v60, 16, v173
	v_and_b32_e32 v61, 0xffff0000, v173
	v_lshlrev_b32_e32 v62, 16, v174
	v_and_b32_e32 v63, 0xffff0000, v174
	v_lshlrev_b32_e32 v64, 16, v175
	v_and_b32_e32 v65, 0xffff0000, v175
	v_lshlrev_b32_e32 v66, 16, v176
	v_and_b32_e32 v67, 0xffff0000, v176
	v_lshlrev_b32_e32 v68, 16, v177
	v_and_b32_e32 v69, 0xffff0000, v177
	v_lshlrev_b32_e32 v70, 16, v178
	v_and_b32_e32 v71, 0xffff0000, v178
	v_lshlrev_b32_e32 v72, 16, v179
	v_and_b32_e32 v73, 0xffff0000, v179
	v_lshlrev_b32_e32 v74, 16, v180
	v_and_b32_e32 v75, 0xffff0000, v180
	v_lshlrev_b32_e32 v76, 16, v181
	v_and_b32_e32 v77, 0xffff0000, v181
	v_lshlrev_b32_e32 v78, 16, v182
	v_and_b32_e32 v79, 0xffff0000, v182
	v_lshlrev_b32_e32 v80, 16, v183
	v_and_b32_e32 v81, 0xffff0000, v183
	v_lshlrev_b32_e32 v82, 16, v184
	v_and_b32_e32 v83, 0xffff0000, v184
	v_lshlrev_b32_e32 v84, 16, v185
	v_and_b32_e32 v85, 0xffff0000, v185
	v_and_b32_e32 v186, s42, v186
	v_and_b32_e32 v187, s42, v187
	v_lshlrev_b32_e32 v86, 16, v186
	v_and_b32_e32 v87, 0xffff0000, v186
	v_lshlrev_b32_e32 v88, 16, v187
	v_and_b32_e32 v89, 0xffff0000, v187
	s_cmp_eq_u32 s32, 3
	s_cbranch_scc1 .Lffn_p9_skipld16
	global_load_dword v172, v1, s[8:9]
	global_load_dword v173, v2, s[8:9]
	s_add_u32 s8, s8, 0x5800
	s_addc_u32 s9, s9, 0
	global_load_dword v174, v1, s[8:9]
	global_load_dword v175, v2, s[8:9]
	s_add_u32 s8, s8, 0x5800
	s_addc_u32 s9, s9, 0
	global_load_dword v176, v1, s[8:9]
	global_load_dword v177, v2, s[8:9]
	s_add_u32 s8, s8, 0x5800
	s_addc_u32 s9, s9, 0
	global_load_dword v178, v1, s[8:9]
	global_load_dword v179, v2, s[8:9]
	s_add_u32 s8, s8, 0x5800
	s_addc_u32 s9, s9, 0
	global_load_dword v180, v1, s[8:9]
	global_load_dword v181, v2, s[8:9]
	s_add_u32 s8, s8, 0x5800
	s_addc_u32 s9, s9, 0
	global_load_dword v182, v1, s[8:9]
	global_load_dword v183, v2, s[8:9]
	s_add_u32 s8, s8, 0x5800
	s_addc_u32 s9, s9, 0
	global_load_dword v184, v1, s[8:9]
	global_load_dword v185, v2, s[8:9]
	s_add_u32 s8, s8, 0x5800
	s_addc_u32 s9, s9, 0
	global_load_dword v186, v1, s[8:9]
	global_load_dword v187, v2, s[8:9]
	s_add_u32 s8, s8, 0x5800
	s_addc_u32 s9, s9, 0
.Lffn_p9_skipld16:
	v_pk_fma_f32 v[146:147], v[16:17], v[50:51], v[46:47]
	v_pk_fma_f32 v[148:149], v[34:35], v[52:53], v[48:49]
	v_pk_fma_f32 v[146:147], v[18:19], v[54:55], v[146:147]
	v_pk_fma_f32 v[148:149], v[36:37], v[56:57], v[148:149]
	v_pk_fma_f32 v[146:147], v[20:21], v[58:59], v[146:147]
	v_pk_fma_f32 v[148:149], v[38:39], v[60:61], v[148:149]
	v_pk_mul_f32 v[150:151], v[146:147], v[4:5]
	v_exp_f32_e32 v150, v150
	v_exp_f32_e32 v151, v151
	s_nop 0
	v_pk_add_f32 v[150:151], v[150:151], v[6:7]
	v_rcp_f32_e32 v150, v150
	v_rcp_f32_e32 v151, v151
	s_nop 0
	v_pk_mul_f32 v[150:151], v[150:151], v[146:147]
	v_pk_mul_f32 v[150:151], v[150:151], v[148:149]
	v_cvt_pk_bf16_f32 v204, v150, v151
	global_store_dword v1, v204, s[20:21]
	s_add_u32 s20, s20, 0x2c00
	s_addc_u32 s21, s21, 0
	v_pk_fma_f32 v[146:147], v[16:17], v[54:55], v[46:47]
	v_pk_fma_f32 v[148:149], v[34:35], v[56:57], v[48:49]
	v_pk_fma_f32 v[146:147], v[18:19], v[58:59], v[146:147]
	v_pk_fma_f32 v[148:149], v[36:37], v[60:61], v[148:149]
	v_pk_fma_f32 v[146:147], v[20:21], v[62:63], v[146:147]
	v_pk_fma_f32 v[148:149], v[38:39], v[64:65], v[148:149]
	v_pk_mul_f32 v[150:151], v[146:147], v[4:5]
	v_exp_f32_e32 v150, v150
	v_exp_f32_e32 v151, v151
	s_nop 0
	v_pk_add_f32 v[150:151], v[150:151], v[6:7]
	v_rcp_f32_e32 v150, v150
	v_rcp_f32_e32 v151, v151
	s_nop 0
	v_pk_mul_f32 v[150:151], v[150:151], v[146:147]
	v_pk_mul_f32 v[150:151], v[150:151], v[148:149]
	v_cvt_pk_bf16_f32 v205, v150, v151
	global_store_dword v1, v205, s[20:21]
	s_add_u32 s20, s20, 0x2c00
	s_addc_u32 s21, s21, 0
	v_pk_fma_f32 v[146:147], v[16:17], v[58:59], v[46:47]
	v_pk_fma_f32 v[148:149], v[34:35], v[60:61], v[48:49]
	v_pk_fma_f32 v[146:147], v[18:19], v[62:63], v[146:147]
	v_pk_fma_f32 v[148:149], v[36:37], v[64:65], v[148:149]
	v_pk_fma_f32 v[146:147], v[20:21], v[66:67], v[146:147]
	v_pk_fma_f32 v[148:149], v[38:39], v[68:69], v[148:149]
	v_pk_mul_f32 v[150:151], v[146:147], v[4:5]
	v_exp_f32_e32 v150, v150
	v_exp_f32_e32 v151, v151
	s_nop 0
	v_pk_add_f32 v[150:151], v[150:151], v[6:7]
	v_rcp_f32_e32 v150, v150
	v_rcp_f32_e32 v151, v151
	s_nop 0
	v_pk_mul_f32 v[150:151], v[150:151], v[146:147]
	v_pk_mul_f32 v[150:151], v[150:151], v[148:149]
	v_cvt_pk_bf16_f32 v206, v150, v151
	global_store_dword v1, v206, s[20:21]
	s_add_u32 s20, s20, 0x2c00
	s_addc_u32 s21, s21, 0
	v_pk_fma_f32 v[146:147], v[16:17], v[62:63], v[46:47]
	v_pk_fma_f32 v[148:149], v[34:35], v[64:65], v[48:49]
	v_pk_fma_f32 v[146:147], v[18:19], v[66:67], v[146:147]
	v_pk_fma_f32 v[148:149], v[36:37], v[68:69], v[148:149]
	v_pk_fma_f32 v[146:147], v[20:21], v[70:71], v[146:147]
	v_pk_fma_f32 v[148:149], v[38:39], v[72:73], v[148:149]
	v_pk_mul_f32 v[150:151], v[146:147], v[4:5]
	v_exp_f32_e32 v150, v150
	v_exp_f32_e32 v151, v151
	s_nop 0
	v_pk_add_f32 v[150:151], v[150:151], v[6:7]
	v_rcp_f32_e32 v150, v150
	v_rcp_f32_e32 v151, v151
	s_nop 0
	v_pk_mul_f32 v[150:151], v[150:151], v[146:147]
	v_pk_mul_f32 v[150:151], v[150:151], v[148:149]
	v_cvt_pk_bf16_f32 v207, v150, v151
	global_store_dword v1, v207, s[20:21]
	s_add_u32 s20, s20, 0x2c00
	s_addc_u32 s21, s21, 0
	v_pk_fma_f32 v[146:147], v[16:17], v[66:67], v[46:47]
	v_pk_fma_f32 v[148:149], v[34:35], v[68:69], v[48:49]
	v_pk_fma_f32 v[146:147], v[18:19], v[70:71], v[146:147]
	v_pk_fma_f32 v[148:149], v[36:37], v[72:73], v[148:149]
	v_pk_fma_f32 v[146:147], v[20:21], v[74:75], v[146:147]
	v_pk_fma_f32 v[148:149], v[38:39], v[76:77], v[148:149]
	v_pk_mul_f32 v[150:151], v[146:147], v[4:5]
	v_exp_f32_e32 v150, v150
	v_exp_f32_e32 v151, v151
	s_nop 0
	v_pk_add_f32 v[150:151], v[150:151], v[6:7]
	v_rcp_f32_e32 v150, v150
	v_rcp_f32_e32 v151, v151
	s_nop 0
	v_pk_mul_f32 v[150:151], v[150:151], v[146:147]
	v_pk_mul_f32 v[150:151], v[150:151], v[148:149]
	v_cvt_pk_bf16_f32 v204, v150, v151
	global_store_dword v1, v204, s[20:21]
	s_add_u32 s20, s20, 0x2c00
	s_addc_u32 s21, s21, 0
	v_pk_fma_f32 v[146:147], v[16:17], v[70:71], v[46:47]
	v_pk_fma_f32 v[148:149], v[34:35], v[72:73], v[48:49]
	v_pk_fma_f32 v[146:147], v[18:19], v[74:75], v[146:147]
	v_pk_fma_f32 v[148:149], v[36:37], v[76:77], v[148:149]
	v_pk_fma_f32 v[146:147], v[20:21], v[78:79], v[146:147]
	v_pk_fma_f32 v[148:149], v[38:39], v[80:81], v[148:149]
	v_pk_mul_f32 v[150:151], v[146:147], v[4:5]
	v_exp_f32_e32 v150, v150
	v_exp_f32_e32 v151, v151
	s_nop 0
	v_pk_add_f32 v[150:151], v[150:151], v[6:7]
	v_rcp_f32_e32 v150, v150
	v_rcp_f32_e32 v151, v151
	s_nop 0
	v_pk_mul_f32 v[150:151], v[150:151], v[146:147]
	v_pk_mul_f32 v[150:151], v[150:151], v[148:149]
	v_cvt_pk_bf16_f32 v205, v150, v151
	global_store_dword v1, v205, s[20:21]
	s_add_u32 s20, s20, 0x2c00
	s_addc_u32 s21, s21, 0
	v_pk_fma_f32 v[146:147], v[16:17], v[74:75], v[46:47]
	v_pk_fma_f32 v[148:149], v[34:35], v[76:77], v[48:49]
	v_pk_fma_f32 v[146:147], v[18:19], v[78:79], v[146:147]
	v_pk_fma_f32 v[148:149], v[36:37], v[80:81], v[148:149]
	v_pk_fma_f32 v[146:147], v[20:21], v[82:83], v[146:147]
	v_pk_fma_f32 v[148:149], v[38:39], v[84:85], v[148:149]
	v_pk_mul_f32 v[150:151], v[146:147], v[4:5]
	v_exp_f32_e32 v150, v150
	v_exp_f32_e32 v151, v151
	s_nop 0
	v_pk_add_f32 v[150:151], v[150:151], v[6:7]
	v_rcp_f32_e32 v150, v150
	v_rcp_f32_e32 v151, v151
	s_nop 0
	v_pk_mul_f32 v[150:151], v[150:151], v[146:147]
	v_pk_mul_f32 v[150:151], v[150:151], v[148:149]
	v_cvt_pk_bf16_f32 v206, v150, v151
	global_store_dword v1, v206, s[20:21]
	s_add_u32 s20, s20, 0x2c00
	s_addc_u32 s21, s21, 0
	v_pk_fma_f32 v[146:147], v[16:17], v[78:79], v[46:47]
	v_pk_fma_f32 v[148:149], v[34:35], v[80:81], v[48:49]
	v_pk_fma_f32 v[146:147], v[18:19], v[82:83], v[146:147]
	v_pk_fma_f32 v[148:149], v[36:37], v[84:85], v[148:149]
	v_pk_fma_f32 v[146:147], v[20:21], v[86:87], v[146:147]
	v_pk_fma_f32 v[148:149], v[38:39], v[88:89], v[148:149]
	v_pk_mul_f32 v[150:151], v[146:147], v[4:5]
	v_exp_f32_e32 v150, v150
	v_exp_f32_e32 v151, v151
	s_nop 0
	v_pk_add_f32 v[150:151], v[150:151], v[6:7]
	v_rcp_f32_e32 v150, v150
	v_rcp_f32_e32 v151, v151
	s_nop 0
	v_pk_mul_f32 v[150:151], v[150:151], v[146:147]
	v_pk_mul_f32 v[150:151], v[150:151], v[148:149]
	v_cvt_pk_bf16_f32 v207, v150, v151
	global_store_dword v1, v207, s[20:21]
	s_add_u32 s20, s20, 0x2c00
	s_addc_u32 s21, s21, 0
	s_add_u32 s32, s32, 1
	s_cmp_lt_u32 s32, 4
	s_cbranch_scc1 .Lffn_p9_loop_ctx9
.Lffn_p9_itemend:
	s_waitcnt vmcnt(0)
	v_readfirstlane_b32 s6, v8
	s_add_u32 s6, s6, 2048
	s_branch .Lffn_p9_item
